# v17: v16 + loader s_setprio 2 issued before the post-MFMA barrier (load segment opens with ds_reads)
# speedup vs baseline: 1.0119x; 1.0016x over previous
.LBB0_271:
	s_add_u32 s26, s14, 0xfffc0080
	s_addc_u32 s27, s15, -1
	s_add_i32 s54, 0, 0x10000
	s_cmp_eq_u32 s53, 12
	s_cselect_b32 s29, s21, s27
	s_cselect_b32 s28, s49, s26
	v_add_u32_e32 v154, s54, v141
	s_cselect_b32 s27, s19, s52
	s_cselect_b32 s26, s50, s51
	s_add_i32 s56, 0, 0x14000
	ds_read_b128 v[146:149], v154
	ds_read_b128 v[150:153], v154 offset:1024
	ds_read_b128 v[162:165], v154 offset:2048
	ds_read_b128 v[166:169], v154 offset:3072
	v_add_u32_e32 v154, s56, v141
	ds_read_b128 v[170:173], v154
	ds_read_b128 v[186:189], v154 offset:1024
	ds_read_b128 v[190:193], v154 offset:2048
	ds_read_b128 v[194:197], v154 offset:3072
	v_lshl_add_u64 v[154:155], s[14:15], 0, v[136:137]
	s_add_i32 m0, s37, 0xc000
	ds_read_b128 v[198:201], v145
	ds_read_b128 v[202:205], v145 offset:1024
	ds_read_b128 v[206:209], v145 offset:2048
	ds_read_b128 v[210:213], v145 offset:3072
	ds_read_b128 v[214:217], v145 offset:4096
	ds_read_b128 v[218:221], v145 offset:5120
	ds_read_b128 v[222:225], v145 offset:6144
	ds_read_b128 v[226:229], v145 offset:7168
	global_load_lds_dwordx4 v[154:155], off
	v_lshl_add_u64 v[154:155], s[14:15], 0, v[138:139]
	s_add_i32 m0, s37, 0xe000
	s_nop 0
	global_load_lds_dwordx4 v[154:155], off
	s_setprio 1
	s_waitcnt vmcnt(8) lgkmcnt(0)
	s_barrier
	v_mfma_f32_16x16x32_bf16 v[126:129], v[146:149], v[198:201], v[126:129]
	v_mfma_f32_16x16x32_bf16 v[122:125], v[162:165], v[198:201], v[122:125]
	v_mfma_f32_16x16x32_bf16 v[110:113], v[146:149], v[206:209], v[110:113]
	v_mfma_f32_16x16x32_bf16 v[106:109], v[162:165], v[206:209], v[106:109]
	v_mfma_f32_16x16x32_bf16 v[92:95], v[146:149], v[214:217], v[92:95]
	v_mfma_f32_16x16x32_bf16 v[88:91], v[162:165], v[214:217], v[88:91]
	v_mfma_f32_16x16x32_bf16 v[76:79], v[146:149], v[222:225], v[76:79]
	v_mfma_f32_16x16x32_bf16 v[72:75], v[162:165], v[222:225], v[72:75]
	v_mfma_f32_16x16x32_bf16 v[126:129], v[150:153], v[202:205], v[126:129]
	v_mfma_f32_16x16x32_bf16 v[122:125], v[166:169], v[202:205], v[122:125]
	v_mfma_f32_16x16x32_bf16 v[110:113], v[150:153], v[210:213], v[110:113]
	v_mfma_f32_16x16x32_bf16 v[106:109], v[166:169], v[210:213], v[106:109]
	v_mfma_f32_16x16x32_bf16 v[92:95], v[150:153], v[218:221], v[92:95]
	v_mfma_f32_16x16x32_bf16 v[88:91], v[166:169], v[218:221], v[88:91]
	v_mfma_f32_16x16x32_bf16 v[76:79], v[150:153], v[226:229], v[76:79]
	v_mfma_f32_16x16x32_bf16 v[72:75], v[166:169], v[226:229], v[72:75]
	s_setprio 0
	s_setprio 1
	v_mfma_f32_16x16x32_bf16 v[118:121], v[170:173], v[198:201], v[118:121]
	v_mfma_f32_16x16x32_bf16 v[114:117], v[190:193], v[198:201], v[114:117]
	v_mfma_f32_16x16x32_bf16 v[102:105], v[170:173], v[206:209], v[102:105]
	v_mfma_f32_16x16x32_bf16 v[98:101], v[190:193], v[206:209], v[98:101]
	v_mfma_f32_16x16x32_bf16 v[84:87], v[170:173], v[214:217], v[84:87]
	v_mfma_f32_16x16x32_bf16 v[80:83], v[190:193], v[214:217], v[80:83]
	v_mfma_f32_16x16x32_bf16 v[68:71], v[170:173], v[222:225], v[68:71]
	v_mfma_f32_16x16x32_bf16 v[64:67], v[190:193], v[222:225], v[64:67]
	v_mfma_f32_16x16x32_bf16 v[118:121], v[186:189], v[202:205], v[118:121]
	v_mfma_f32_16x16x32_bf16 v[114:117], v[194:197], v[202:205], v[114:117]
	v_mfma_f32_16x16x32_bf16 v[102:105], v[186:189], v[210:213], v[102:105]
	v_mfma_f32_16x16x32_bf16 v[98:101], v[194:197], v[210:213], v[98:101]
	v_mfma_f32_16x16x32_bf16 v[84:87], v[186:189], v[218:221], v[84:87]
	v_mfma_f32_16x16x32_bf16 v[80:83], v[194:197], v[218:221], v[80:83]
	v_mfma_f32_16x16x32_bf16 v[68:71], v[186:189], v[226:229], v[68:71]
	v_mfma_f32_16x16x32_bf16 v[64:67], v[194:197], v[226:229], v[64:67]
	s_setprio 2
	s_barrier
	s_add_i32 s54, s54, s36
	v_lshl_add_u64 v[154:155], s[26:27], 0, v[96:97]
	s_mov_b32 m0, s54
	ds_read_b128 v[198:201], v145 offset:16384
	ds_read_b128 v[202:205], v145 offset:17408
	ds_read_b128 v[206:209], v145 offset:18432
	ds_read_b128 v[210:213], v145 offset:19456
	ds_read_b128 v[214:217], v145 offset:20480
	ds_read_b128 v[218:221], v145 offset:21504
	ds_read_b128 v[222:225], v145 offset:22528
	ds_read_b128 v[226:229], v145 offset:23552
	global_load_lds_dwordx4 v[154:155], off
	s_add_i32 m0, s54, 0x2000
	s_add_u32 s54, s26, 0x40000
	v_lshl_add_u64 v[156:157], s[26:27], 0, v[130:131]
	s_addc_u32 s55, s27, 0
	s_add_i32 s56, s56, s36
	global_load_lds_dwordx4 v[156:157], off
	v_lshl_add_u64 v[158:159], s[54:55], 0, v[96:97]
	s_mov_b32 m0, s56
	v_lshl_add_u64 v[182:183], s[28:29], 0, v[132:133]
	global_load_lds_dwordx4 v[158:159], off
	v_lshl_add_u64 v[158:159], s[54:55], 0, v[130:131]
	s_add_i32 m0, s56, 0x2000
	s_nop 0
	global_load_lds_dwordx4 v[158:159], off
	v_lshl_add_u64 v[158:159], s[28:29], 0, v[134:135]
	s_mov_b32 m0, s37
	s_nop 0
	global_load_lds_dwordx4 v[158:159], off
	s_mov_b32 m0, s38
	s_nop 0
	global_load_lds_dwordx4 v[182:183], off
	s_setprio 1
	s_waitcnt vmcnt(8) lgkmcnt(0)
	s_barrier
	v_mfma_f32_16x16x32_bf16 v[60:63], v[146:149], v[198:201], v[60:63]
	v_mfma_f32_16x16x32_bf16 v[56:59], v[162:165], v[198:201], v[56:59]
	v_mfma_f32_16x16x32_bf16 v[44:47], v[146:149], v[206:209], v[44:47]
	v_mfma_f32_16x16x32_bf16 v[40:43], v[162:165], v[206:209], v[40:43]
	v_mfma_f32_16x16x32_bf16 v[28:31], v[146:149], v[214:217], v[28:31]
	v_mfma_f32_16x16x32_bf16 v[24:27], v[162:165], v[214:217], v[24:27]
	v_mfma_f32_16x16x32_bf16 v[12:15], v[146:149], v[222:225], v[12:15]
	v_mfma_f32_16x16x32_bf16 v[4:7], v[162:165], v[222:225], v[4:7]
	v_mfma_f32_16x16x32_bf16 v[60:63], v[150:153], v[202:205], v[60:63]
	v_mfma_f32_16x16x32_bf16 v[56:59], v[166:169], v[202:205], v[56:59]
	v_mfma_f32_16x16x32_bf16 v[44:47], v[150:153], v[210:213], v[44:47]
	v_mfma_f32_16x16x32_bf16 v[40:43], v[166:169], v[210:213], v[40:43]
	v_mfma_f32_16x16x32_bf16 v[28:31], v[150:153], v[218:221], v[28:31]
	v_mfma_f32_16x16x32_bf16 v[24:27], v[166:169], v[218:221], v[24:27]
	v_mfma_f32_16x16x32_bf16 v[12:15], v[150:153], v[226:229], v[12:15]
	v_mfma_f32_16x16x32_bf16 v[4:7], v[166:169], v[226:229], v[4:7]
	s_setprio 0
	s_setprio 1
	v_mfma_f32_16x16x32_bf16 v[52:55], v[170:173], v[198:201], v[52:55]
	v_mfma_f32_16x16x32_bf16 v[48:51], v[190:193], v[198:201], v[48:51]
	v_mfma_f32_16x16x32_bf16 v[36:39], v[170:173], v[206:209], v[36:39]
	v_mfma_f32_16x16x32_bf16 v[32:35], v[190:193], v[206:209], v[32:35]
	v_mfma_f32_16x16x32_bf16 v[20:23], v[170:173], v[214:217], v[20:23]
	v_mfma_f32_16x16x32_bf16 v[16:19], v[190:193], v[214:217], v[16:19]
	v_mfma_f32_16x16x32_bf16 v[8:11], v[170:173], v[222:225], v[8:11]
	v_mfma_f32_16x16x32_bf16 v[0:3], v[190:193], v[222:225], v[0:3]
	v_mfma_f32_16x16x32_bf16 v[52:55], v[186:189], v[202:205], v[52:55]
	v_mfma_f32_16x16x32_bf16 v[48:51], v[194:197], v[202:205], v[48:51]
	v_mfma_f32_16x16x32_bf16 v[36:39], v[186:189], v[210:213], v[36:39]
	v_mfma_f32_16x16x32_bf16 v[32:35], v[194:197], v[210:213], v[32:35]
	v_mfma_f32_16x16x32_bf16 v[20:23], v[186:189], v[218:221], v[20:23]
	v_mfma_f32_16x16x32_bf16 v[16:19], v[194:197], v[218:221], v[16:19]
	v_mfma_f32_16x16x32_bf16 v[8:11], v[186:189], v[226:229], v[8:11]
	v_mfma_f32_16x16x32_bf16 v[0:3], v[194:197], v[226:229], v[0:3]
	s_setprio 2
	s_barrier
	s_add_i32 s54, 0, 0x18000
	s_add_i32 s55, 0, 0x1c000
	v_add_u32_e32 v166, s54, v141
	v_add_u32_e32 v184, s55, v141
	ds_read_b128 v[146:149], v166
	ds_read_b128 v[150:153], v166 offset:1024
	ds_read_b128 v[162:165], v166 offset:2048
	ds_read_b128 v[166:169], v166 offset:3072
	ds_read_b128 v[170:173], v184
	ds_read_b128 v[186:189], v184 offset:1024
	ds_read_b128 v[190:193], v184 offset:2048
	ds_read_b128 v[194:197], v184 offset:3072
	s_add_u32 s28, s28, 0x40000
	s_addc_u32 s29, s29, 0
	s_mov_b32 m0, s39
	v_lshl_add_u64 v[184:185], s[28:29], 0, v[134:135]
	ds_read_b128 v[198:201], v145 offset:32768
	ds_read_b128 v[202:205], v145 offset:33792
	ds_read_b128 v[206:209], v145 offset:34816
	ds_read_b128 v[210:213], v145 offset:35840
	ds_read_b128 v[214:217], v145 offset:36864
	ds_read_b128 v[218:221], v145 offset:37888
	ds_read_b128 v[222:225], v145 offset:38912
	ds_read_b128 v[226:229], v145 offset:39936
	global_load_lds_dwordx4 v[184:185], off
	v_lshl_add_u64 v[184:185], s[28:29], 0, v[132:133]
	s_mov_b32 m0, s40
	s_nop 0
	global_load_lds_dwordx4 v[184:185], off
	s_setprio 1
	s_waitcnt vmcnt(8) lgkmcnt(0)
	s_barrier
	v_mfma_f32_16x16x32_bf16 v[126:129], v[146:149], v[198:201], v[126:129]
	v_mfma_f32_16x16x32_bf16 v[122:125], v[162:165], v[198:201], v[122:125]
	v_mfma_f32_16x16x32_bf16 v[110:113], v[146:149], v[206:209], v[110:113]
	v_mfma_f32_16x16x32_bf16 v[106:109], v[162:165], v[206:209], v[106:109]
	v_mfma_f32_16x16x32_bf16 v[92:95], v[146:149], v[214:217], v[92:95]
	v_mfma_f32_16x16x32_bf16 v[88:91], v[162:165], v[214:217], v[88:91]
	v_mfma_f32_16x16x32_bf16 v[76:79], v[146:149], v[222:225], v[76:79]
	v_mfma_f32_16x16x32_bf16 v[72:75], v[162:165], v[222:225], v[72:75]
	v_mfma_f32_16x16x32_bf16 v[126:129], v[150:153], v[202:205], v[126:129]
	v_mfma_f32_16x16x32_bf16 v[122:125], v[166:169], v[202:205], v[122:125]
	v_mfma_f32_16x16x32_bf16 v[110:113], v[150:153], v[210:213], v[110:113]
	v_mfma_f32_16x16x32_bf16 v[106:109], v[166:169], v[210:213], v[106:109]
	v_mfma_f32_16x16x32_bf16 v[92:95], v[150:153], v[218:221], v[92:95]
	v_mfma_f32_16x16x32_bf16 v[88:91], v[166:169], v[218:221], v[88:91]
	v_mfma_f32_16x16x32_bf16 v[76:79], v[150:153], v[226:229], v[76:79]
	v_mfma_f32_16x16x32_bf16 v[72:75], v[166:169], v[226:229], v[72:75]
	s_setprio 0
	s_setprio 1
	v_mfma_f32_16x16x32_bf16 v[118:121], v[170:173], v[198:201], v[118:121]
	v_mfma_f32_16x16x32_bf16 v[114:117], v[190:193], v[198:201], v[114:117]
	v_mfma_f32_16x16x32_bf16 v[102:105], v[170:173], v[206:209], v[102:105]
	v_mfma_f32_16x16x32_bf16 v[98:101], v[190:193], v[206:209], v[98:101]
	v_mfma_f32_16x16x32_bf16 v[84:87], v[170:173], v[214:217], v[84:87]
	v_mfma_f32_16x16x32_bf16 v[80:83], v[190:193], v[214:217], v[80:83]
	v_mfma_f32_16x16x32_bf16 v[68:71], v[170:173], v[222:225], v[68:71]
	v_mfma_f32_16x16x32_bf16 v[64:67], v[190:193], v[222:225], v[64:67]
	v_mfma_f32_16x16x32_bf16 v[118:121], v[186:189], v[202:205], v[118:121]
	v_mfma_f32_16x16x32_bf16 v[114:117], v[194:197], v[202:205], v[114:117]
	v_mfma_f32_16x16x32_bf16 v[102:105], v[186:189], v[210:213], v[102:105]
	v_mfma_f32_16x16x32_bf16 v[98:101], v[194:197], v[210:213], v[98:101]
	v_mfma_f32_16x16x32_bf16 v[84:87], v[186:189], v[218:221], v[84:87]
	v_mfma_f32_16x16x32_bf16 v[80:83], v[194:197], v[218:221], v[80:83]
	v_mfma_f32_16x16x32_bf16 v[68:71], v[186:189], v[226:229], v[68:71]
	v_mfma_f32_16x16x32_bf16 v[64:67], v[194:197], v[226:229], v[64:67]
	s_setprio 2
	s_barrier
	s_add_i32 s28, s54, s36
	v_lshl_add_u64 v[154:155], v[154:155], 0, s[16:17]
	s_mov_b32 m0, s28
	ds_read_b128 v[198:201], v145 offset:49152
	ds_read_b128 v[202:205], v145 offset:50176
	ds_read_b128 v[206:209], v145 offset:51200
	ds_read_b128 v[210:213], v145 offset:52224
	ds_read_b128 v[214:217], v145 offset:53248
	ds_read_b128 v[218:221], v145 offset:54272
	ds_read_b128 v[222:225], v145 offset:55296
	ds_read_b128 v[226:229], v145 offset:56320
	global_load_lds_dwordx4 v[154:155], off
	s_add_i32 m0, s28, 0x2000
	s_add_u32 s26, s26, 0x40080
	v_lshl_add_u64 v[154:155], v[156:157], 0, s[16:17]
	s_addc_u32 s27, s27, 0
	s_add_i32 s28, s55, s36
	global_load_lds_dwordx4 v[154:155], off
	v_lshl_add_u64 v[154:155], s[26:27], 0, v[96:97]
	s_mov_b32 m0, s28
	s_nop 0
	global_load_lds_dwordx4 v[154:155], off
	v_lshl_add_u64 v[154:155], s[26:27], 0, v[130:131]
	s_add_i32 m0, s28, 0x2000
	s_nop 0
	global_load_lds_dwordx4 v[154:155], off
	v_lshl_add_u64 v[154:155], v[158:159], 0, s[16:17]
	s_mov_b32 m0, s41
	s_nop 0
	global_load_lds_dwordx4 v[154:155], off
	v_lshl_add_u64 v[154:155], v[182:183], 0, s[16:17]
	s_mov_b32 m0, s42
	s_nop 0
	global_load_lds_dwordx4 v[154:155], off
	s_setprio 1
	s_waitcnt vmcnt(8) lgkmcnt(0)
	s_barrier
	v_mfma_f32_16x16x32_bf16 v[60:63], v[146:149], v[198:201], v[60:63]
	v_mfma_f32_16x16x32_bf16 v[56:59], v[162:165], v[198:201], v[56:59]
	v_mfma_f32_16x16x32_bf16 v[44:47], v[146:149], v[206:209], v[44:47]
	v_mfma_f32_16x16x32_bf16 v[40:43], v[162:165], v[206:209], v[40:43]
	v_mfma_f32_16x16x32_bf16 v[28:31], v[146:149], v[214:217], v[28:31]
	v_mfma_f32_16x16x32_bf16 v[24:27], v[162:165], v[214:217], v[24:27]
	v_mfma_f32_16x16x32_bf16 v[12:15], v[146:149], v[222:225], v[12:15]
	v_mfma_f32_16x16x32_bf16 v[4:7], v[162:165], v[222:225], v[4:7]
	v_mfma_f32_16x16x32_bf16 v[60:63], v[150:153], v[202:205], v[60:63]
	v_mfma_f32_16x16x32_bf16 v[56:59], v[166:169], v[202:205], v[56:59]
	v_mfma_f32_16x16x32_bf16 v[44:47], v[150:153], v[210:213], v[44:47]
	v_mfma_f32_16x16x32_bf16 v[40:43], v[166:169], v[210:213], v[40:43]
	v_mfma_f32_16x16x32_bf16 v[28:31], v[150:153], v[218:221], v[28:31]
	v_mfma_f32_16x16x32_bf16 v[24:27], v[166:169], v[218:221], v[24:27]
	v_mfma_f32_16x16x32_bf16 v[12:15], v[150:153], v[226:229], v[12:15]
	v_mfma_f32_16x16x32_bf16 v[4:7], v[166:169], v[226:229], v[4:7]
	s_setprio 0
	s_setprio 1
	v_mfma_f32_16x16x32_bf16 v[52:55], v[170:173], v[198:201], v[52:55]
	v_mfma_f32_16x16x32_bf16 v[48:51], v[190:193], v[198:201], v[48:51]
	v_mfma_f32_16x16x32_bf16 v[36:39], v[170:173], v[206:209], v[36:39]
	v_mfma_f32_16x16x32_bf16 v[32:35], v[190:193], v[206:209], v[32:35]
	v_mfma_f32_16x16x32_bf16 v[20:23], v[170:173], v[214:217], v[20:23]
	v_mfma_f32_16x16x32_bf16 v[16:19], v[190:193], v[214:217], v[16:19]
	v_mfma_f32_16x16x32_bf16 v[8:11], v[170:173], v[222:225], v[8:11]
	v_mfma_f32_16x16x32_bf16 v[0:3], v[190:193], v[222:225], v[0:3]
	v_mfma_f32_16x16x32_bf16 v[52:55], v[186:189], v[202:205], v[52:55]
	v_mfma_f32_16x16x32_bf16 v[48:51], v[194:197], v[202:205], v[48:51]
	v_mfma_f32_16x16x32_bf16 v[36:39], v[186:189], v[210:213], v[36:39]
	v_mfma_f32_16x16x32_bf16 v[32:35], v[194:197], v[210:213], v[32:35]
	v_mfma_f32_16x16x32_bf16 v[20:23], v[186:189], v[218:221], v[20:23]
	v_mfma_f32_16x16x32_bf16 v[16:19], v[194:197], v[218:221], v[16:19]
	v_mfma_f32_16x16x32_bf16 v[8:11], v[186:189], v[226:229], v[8:11]
	v_mfma_f32_16x16x32_bf16 v[0:3], v[194:197], v[226:229], v[0:3]
	s_setprio 2
	s_barrier
	s_add_i32 s53, s53, 2
	s_add_u32 s14, s14, 0x100
	s_addc_u32 s15, s15, 0
	s_add_u32 s51, s51, 0x100
	s_addc_u32 s52, s52, 0
	s_cmp_gt_u32 s53, 13
	s_cbranch_scc0 .LBB0_271
	s_and_b64 vcc, exec, s[12:13]
	s_cbranch_vccz .LBB0_274
	s_barrier

.LBB0_361:
	s_add_u32 s34, s30, 0xfffc0080
	s_addc_u32 s35, s31, -1
	s_add_i32 s62, 0, 0x10000
	s_cmp_eq_u32 s61, 12
	s_cselect_b32 s37, s25, s35
	s_cselect_b32 s36, s57, s34
	v_add_u32_e32 v96, s62, v151
	s_cselect_b32 s35, s15, s60
	s_cselect_b32 s34, s58, s59
	s_add_i32 s64, 0, 0x14000
	ds_read_b128 v[164:167], v96
	ds_read_b128 v[168:171], v96 offset:1024
	ds_read_b128 v[186:189], v96 offset:2048
	ds_read_b128 v[190:193], v96 offset:3072
	v_add_u32_e32 v96, s64, v151
	ds_read_b128 v[194:197], v96
	ds_read_b128 v[198:201], v96 offset:1024
	ds_read_b128 v[202:205], v96 offset:2048
	ds_read_b128 v[206:209], v96 offset:3072
	v_lshl_add_u64 v[154:155], s[30:31], 0, v[146:147]
	s_add_i32 m0, s43, 0xc000
	ds_read_b128 v[210:213], v162
	ds_read_b128 v[214:217], v162 offset:1024
	ds_read_b128 v[218:221], v162 offset:2048
	ds_read_b128 v[222:225], v162 offset:3072
	ds_read_b128 v[226:229], v162 offset:4096
	ds_read_b128 v[230:233], v162 offset:5120
	ds_read_b128 v[242:245], v162 offset:6144
	ds_read_b128 v[246:249], v162 offset:7168
	global_load_lds_dwordx4 v[154:155], off
	v_lshl_add_u64 v[154:155], s[30:31], 0, v[148:149]
	s_add_i32 m0, s43, 0xe000
	s_nop 0
	global_load_lds_dwordx4 v[154:155], off
	s_setprio 1
	s_waitcnt vmcnt(8) lgkmcnt(0)
	s_barrier
	v_mfma_f32_16x16x32_bf16 v[126:129], v[164:167], v[210:213], v[126:129]
	v_mfma_f32_16x16x32_bf16 v[122:125], v[186:189], v[210:213], v[122:125]
	v_mfma_f32_16x16x32_bf16 v[118:121], v[164:167], v[218:221], v[118:121]
	v_mfma_f32_16x16x32_bf16 v[114:117], v[186:189], v[218:221], v[114:117]
	v_mfma_f32_16x16x32_bf16 v[110:113], v[164:167], v[226:229], v[110:113]
	v_mfma_f32_16x16x32_bf16 v[106:109], v[186:189], v[226:229], v[106:109]
	v_mfma_f32_16x16x32_bf16 v[102:105], v[164:167], v[242:245], v[102:105]
	v_mfma_f32_16x16x32_bf16 v[98:101], v[186:189], v[242:245], v[98:101]
	v_mfma_f32_16x16x32_bf16 v[126:129], v[168:171], v[214:217], v[126:129]
	v_mfma_f32_16x16x32_bf16 v[122:125], v[190:193], v[214:217], v[122:125]
	v_mfma_f32_16x16x32_bf16 v[118:121], v[168:171], v[222:225], v[118:121]
	v_mfma_f32_16x16x32_bf16 v[114:117], v[190:193], v[222:225], v[114:117]
	v_mfma_f32_16x16x32_bf16 v[110:113], v[168:171], v[230:233], v[110:113]
	v_mfma_f32_16x16x32_bf16 v[106:109], v[190:193], v[230:233], v[106:109]
	v_mfma_f32_16x16x32_bf16 v[102:105], v[168:171], v[246:249], v[102:105]
	v_mfma_f32_16x16x32_bf16 v[98:101], v[190:193], v[246:249], v[98:101]
	s_setprio 0
	s_setprio 1
	v_mfma_f32_16x16x32_bf16 v[76:79], v[194:197], v[210:213], v[76:79]
	v_mfma_f32_16x16x32_bf16 v[64:67], v[202:205], v[210:213], v[64:67]
	v_mfma_f32_16x16x32_bf16 v[60:63], v[194:197], v[218:221], v[60:63]
	v_mfma_f32_16x16x32_bf16 v[52:55], v[202:205], v[218:221], v[52:55]
	v_mfma_f32_16x16x32_bf16 v[44:47], v[194:197], v[226:229], v[44:47]
	v_mfma_f32_16x16x32_bf16 v[40:43], v[202:205], v[226:229], v[40:43]
	v_mfma_f32_16x16x32_bf16 v[36:39], v[194:197], v[242:245], v[36:39]
	v_mfma_f32_16x16x32_bf16 v[32:35], v[202:205], v[242:245], v[32:35]
	v_mfma_f32_16x16x32_bf16 v[76:79], v[198:201], v[214:217], v[76:79]
	v_mfma_f32_16x16x32_bf16 v[64:67], v[206:209], v[214:217], v[64:67]
	v_mfma_f32_16x16x32_bf16 v[60:63], v[198:201], v[222:225], v[60:63]
	v_mfma_f32_16x16x32_bf16 v[52:55], v[206:209], v[222:225], v[52:55]
	v_mfma_f32_16x16x32_bf16 v[44:47], v[198:201], v[230:233], v[44:47]
	v_mfma_f32_16x16x32_bf16 v[40:43], v[206:209], v[230:233], v[40:43]
	v_mfma_f32_16x16x32_bf16 v[36:39], v[198:201], v[246:249], v[36:39]
	v_mfma_f32_16x16x32_bf16 v[32:35], v[206:209], v[246:249], v[32:35]
	s_setprio 2
	s_barrier
	s_add_i32 s62, s62, s40
	v_lshl_add_u64 v[154:155], s[34:35], 0, v[134:135]
	s_mov_b32 m0, s62
	ds_read_b128 v[210:213], v162 offset:16384
	ds_read_b128 v[214:217], v162 offset:17408
	ds_read_b128 v[218:221], v162 offset:18432
	ds_read_b128 v[222:225], v162 offset:19456
	ds_read_b128 v[226:229], v162 offset:20480
	ds_read_b128 v[230:233], v162 offset:21504
	ds_read_b128 v[242:245], v162 offset:22528
	ds_read_b128 v[246:249], v162 offset:23552
	global_load_lds_dwordx4 v[154:155], off
	s_add_i32 m0, s62, 0x2000
	s_add_u32 s62, s34, 0x40000
	v_lshl_add_u64 v[156:157], s[34:35], 0, v[130:131]
	s_addc_u32 s63, s35, 0
	s_add_i32 s64, s64, s40
	global_load_lds_dwordx4 v[156:157], off
	v_lshl_add_u64 v[158:159], s[62:63], 0, v[134:135]
	s_mov_b32 m0, s64
	v_lshl_add_u64 v[172:173], s[36:37], 0, v[132:133]
	global_load_lds_dwordx4 v[158:159], off
	v_lshl_add_u64 v[158:159], s[62:63], 0, v[130:131]
	s_add_i32 m0, s64, 0x2000
	s_nop 0
	global_load_lds_dwordx4 v[158:159], off
	v_lshl_add_u64 v[158:159], s[36:37], 0, v[136:137]
	s_mov_b32 m0, s43
	s_nop 0
	global_load_lds_dwordx4 v[158:159], off
	s_mov_b32 m0, s44
	s_nop 0
	global_load_lds_dwordx4 v[172:173], off
	s_setprio 1
	s_waitcnt vmcnt(8) lgkmcnt(0)
	s_barrier
	v_mfma_f32_16x16x32_bf16 v[92:95], v[164:167], v[210:213], v[92:95]
	v_mfma_f32_16x16x32_bf16 v[88:91], v[186:189], v[210:213], v[88:91]
	v_mfma_f32_16x16x32_bf16 v[84:87], v[164:167], v[218:221], v[84:87]
	v_mfma_f32_16x16x32_bf16 v[80:83], v[186:189], v[218:221], v[80:83]
	v_mfma_f32_16x16x32_bf16 v[72:75], v[164:167], v[226:229], v[72:75]
	v_mfma_f32_16x16x32_bf16 v[68:71], v[186:189], v[226:229], v[68:71]
	v_mfma_f32_16x16x32_bf16 v[56:59], v[164:167], v[242:245], v[56:59]
	v_mfma_f32_16x16x32_bf16 v[48:51], v[186:189], v[242:245], v[48:51]
	v_mfma_f32_16x16x32_bf16 v[92:95], v[168:171], v[214:217], v[92:95]
	v_mfma_f32_16x16x32_bf16 v[88:91], v[190:193], v[214:217], v[88:91]
	v_mfma_f32_16x16x32_bf16 v[84:87], v[168:171], v[222:225], v[84:87]
	v_mfma_f32_16x16x32_bf16 v[80:83], v[190:193], v[222:225], v[80:83]
	v_mfma_f32_16x16x32_bf16 v[72:75], v[168:171], v[230:233], v[72:75]
	v_mfma_f32_16x16x32_bf16 v[68:71], v[190:193], v[230:233], v[68:71]
	v_mfma_f32_16x16x32_bf16 v[56:59], v[168:171], v[246:249], v[56:59]
	v_mfma_f32_16x16x32_bf16 v[48:51], v[190:193], v[246:249], v[48:51]
	s_setprio 0
	s_setprio 1
	v_mfma_f32_16x16x32_bf16 v[28:31], v[194:197], v[210:213], v[28:31]
	v_mfma_f32_16x16x32_bf16 v[24:27], v[202:205], v[210:213], v[24:27]
	v_mfma_f32_16x16x32_bf16 v[20:23], v[194:197], v[218:221], v[20:23]
	v_mfma_f32_16x16x32_bf16 v[16:19], v[202:205], v[218:221], v[16:19]
	v_mfma_f32_16x16x32_bf16 v[12:15], v[194:197], v[226:229], v[12:15]
	v_mfma_f32_16x16x32_bf16 v[8:11], v[202:205], v[226:229], v[8:11]
	v_mfma_f32_16x16x32_bf16 v[4:7], v[194:197], v[242:245], v[4:7]
	v_mfma_f32_16x16x32_bf16 v[0:3], v[202:205], v[242:245], v[0:3]
	v_mfma_f32_16x16x32_bf16 v[28:31], v[198:201], v[214:217], v[28:31]
	v_mfma_f32_16x16x32_bf16 v[24:27], v[206:209], v[214:217], v[24:27]
	v_mfma_f32_16x16x32_bf16 v[20:23], v[198:201], v[222:225], v[20:23]
	v_mfma_f32_16x16x32_bf16 v[16:19], v[206:209], v[222:225], v[16:19]
	v_mfma_f32_16x16x32_bf16 v[12:15], v[198:201], v[230:233], v[12:15]
	v_mfma_f32_16x16x32_bf16 v[8:11], v[206:209], v[230:233], v[8:11]
	v_mfma_f32_16x16x32_bf16 v[4:7], v[198:201], v[246:249], v[4:7]
	v_mfma_f32_16x16x32_bf16 v[0:3], v[206:209], v[246:249], v[0:3]
	s_setprio 2
	s_barrier
	s_add_i32 s62, 0, 0x18000
	v_add_u32_e32 v96, s62, v151
	s_add_i32 s63, 0, 0x1c000
	ds_read_b128 v[164:167], v96
	ds_read_b128 v[168:171], v96 offset:1024
	ds_read_b128 v[186:189], v96 offset:2048
	ds_read_b128 v[190:193], v96 offset:3072
	v_add_u32_e32 v96, s63, v151
	ds_read_b128 v[194:197], v96
	ds_read_b128 v[198:201], v96 offset:1024
	ds_read_b128 v[202:205], v96 offset:2048
	ds_read_b128 v[206:209], v96 offset:3072
	s_add_u32 s36, s36, 0x40000
	s_addc_u32 s37, s37, 0
	s_mov_b32 m0, s45
	v_lshl_add_u64 v[182:183], s[36:37], 0, v[136:137]
	ds_read_b128 v[210:213], v162 offset:32768
	ds_read_b128 v[214:217], v162 offset:33792
	ds_read_b128 v[218:221], v162 offset:34816
	ds_read_b128 v[222:225], v162 offset:35840
	ds_read_b128 v[226:229], v162 offset:36864
	ds_read_b128 v[230:233], v162 offset:37888
	ds_read_b128 v[242:245], v162 offset:38912
	ds_read_b128 v[246:249], v162 offset:39936
	global_load_lds_dwordx4 v[182:183], off
	v_lshl_add_u64 v[182:183], s[36:37], 0, v[132:133]
	s_mov_b32 m0, s46
	s_nop 0
	global_load_lds_dwordx4 v[182:183], off
	s_setprio 1
	s_waitcnt vmcnt(8) lgkmcnt(0)
	s_barrier
	v_mfma_f32_16x16x32_bf16 v[126:129], v[164:167], v[210:213], v[126:129]
	v_mfma_f32_16x16x32_bf16 v[122:125], v[186:189], v[210:213], v[122:125]
	v_mfma_f32_16x16x32_bf16 v[118:121], v[164:167], v[218:221], v[118:121]
	v_mfma_f32_16x16x32_bf16 v[114:117], v[186:189], v[218:221], v[114:117]
	v_mfma_f32_16x16x32_bf16 v[110:113], v[164:167], v[226:229], v[110:113]
	v_mfma_f32_16x16x32_bf16 v[106:109], v[186:189], v[226:229], v[106:109]
	v_mfma_f32_16x16x32_bf16 v[102:105], v[164:167], v[242:245], v[102:105]
	v_mfma_f32_16x16x32_bf16 v[98:101], v[186:189], v[242:245], v[98:101]
	v_mfma_f32_16x16x32_bf16 v[126:129], v[168:171], v[214:217], v[126:129]
	v_mfma_f32_16x16x32_bf16 v[122:125], v[190:193], v[214:217], v[122:125]
	v_mfma_f32_16x16x32_bf16 v[118:121], v[168:171], v[222:225], v[118:121]
	v_mfma_f32_16x16x32_bf16 v[114:117], v[190:193], v[222:225], v[114:117]
	v_mfma_f32_16x16x32_bf16 v[110:113], v[168:171], v[230:233], v[110:113]
	v_mfma_f32_16x16x32_bf16 v[106:109], v[190:193], v[230:233], v[106:109]
	v_mfma_f32_16x16x32_bf16 v[102:105], v[168:171], v[246:249], v[102:105]
	v_mfma_f32_16x16x32_bf16 v[98:101], v[190:193], v[246:249], v[98:101]
	s_setprio 0
	s_setprio 1
	v_mfma_f32_16x16x32_bf16 v[76:79], v[194:197], v[210:213], v[76:79]
	v_mfma_f32_16x16x32_bf16 v[64:67], v[202:205], v[210:213], v[64:67]
	v_mfma_f32_16x16x32_bf16 v[60:63], v[194:197], v[218:221], v[60:63]
	v_mfma_f32_16x16x32_bf16 v[52:55], v[202:205], v[218:221], v[52:55]
	v_mfma_f32_16x16x32_bf16 v[44:47], v[194:197], v[226:229], v[44:47]
	v_mfma_f32_16x16x32_bf16 v[40:43], v[202:205], v[226:229], v[40:43]
	v_mfma_f32_16x16x32_bf16 v[36:39], v[194:197], v[242:245], v[36:39]
	v_mfma_f32_16x16x32_bf16 v[32:35], v[202:205], v[242:245], v[32:35]
	v_mfma_f32_16x16x32_bf16 v[76:79], v[198:201], v[214:217], v[76:79]
	v_mfma_f32_16x16x32_bf16 v[64:67], v[206:209], v[214:217], v[64:67]
	v_mfma_f32_16x16x32_bf16 v[60:63], v[198:201], v[222:225], v[60:63]
	v_mfma_f32_16x16x32_bf16 v[52:55], v[206:209], v[222:225], v[52:55]
	v_mfma_f32_16x16x32_bf16 v[44:47], v[198:201], v[230:233], v[44:47]
	v_mfma_f32_16x16x32_bf16 v[40:43], v[206:209], v[230:233], v[40:43]
	v_mfma_f32_16x16x32_bf16 v[36:39], v[198:201], v[246:249], v[36:39]
	v_mfma_f32_16x16x32_bf16 v[32:35], v[206:209], v[246:249], v[32:35]
	s_setprio 2
	s_barrier
	s_add_i32 s36, s62, s40
	v_lshl_add_u64 v[154:155], v[154:155], 0, s[16:17]
	s_mov_b32 m0, s36
	ds_read_b128 v[210:213], v162 offset:49152
	ds_read_b128 v[214:217], v162 offset:50176
	ds_read_b128 v[218:221], v162 offset:51200
	ds_read_b128 v[222:225], v162 offset:52224
	ds_read_b128 v[226:229], v162 offset:53248
	ds_read_b128 v[230:233], v162 offset:54272
	ds_read_b128 v[242:245], v162 offset:55296
	ds_read_b128 v[246:249], v162 offset:56320
	global_load_lds_dwordx4 v[154:155], off
	s_add_i32 m0, s36, 0x2000
	s_add_u32 s34, s34, 0x40080
	v_lshl_add_u64 v[154:155], v[156:157], 0, s[16:17]
	s_addc_u32 s35, s35, 0
	s_add_i32 s36, s63, s40
	global_load_lds_dwordx4 v[154:155], off
	v_lshl_add_u64 v[154:155], s[34:35], 0, v[134:135]
	s_mov_b32 m0, s36
	s_nop 0
	global_load_lds_dwordx4 v[154:155], off
	v_lshl_add_u64 v[154:155], s[34:35], 0, v[130:131]
	s_add_i32 m0, s36, 0x2000
	s_nop 0
	global_load_lds_dwordx4 v[154:155], off
	v_lshl_add_u64 v[154:155], v[158:159], 0, s[16:17]
	s_mov_b32 m0, s50
	s_nop 0
	global_load_lds_dwordx4 v[154:155], off
	v_lshl_add_u64 v[154:155], v[172:173], 0, s[16:17]
	s_mov_b32 m0, s51
	s_nop 0
	global_load_lds_dwordx4 v[154:155], off
	s_setprio 1
	s_waitcnt vmcnt(8) lgkmcnt(0)
	s_barrier
	v_mfma_f32_16x16x32_bf16 v[92:95], v[164:167], v[210:213], v[92:95]
	v_mfma_f32_16x16x32_bf16 v[88:91], v[186:189], v[210:213], v[88:91]
	v_mfma_f32_16x16x32_bf16 v[84:87], v[164:167], v[218:221], v[84:87]
	v_mfma_f32_16x16x32_bf16 v[80:83], v[186:189], v[218:221], v[80:83]
	v_mfma_f32_16x16x32_bf16 v[72:75], v[164:167], v[226:229], v[72:75]
	v_mfma_f32_16x16x32_bf16 v[68:71], v[186:189], v[226:229], v[68:71]
	v_mfma_f32_16x16x32_bf16 v[56:59], v[164:167], v[242:245], v[56:59]
	v_mfma_f32_16x16x32_bf16 v[48:51], v[186:189], v[242:245], v[48:51]
	v_mfma_f32_16x16x32_bf16 v[92:95], v[168:171], v[214:217], v[92:95]
	v_mfma_f32_16x16x32_bf16 v[88:91], v[190:193], v[214:217], v[88:91]
	v_mfma_f32_16x16x32_bf16 v[84:87], v[168:171], v[222:225], v[84:87]
	v_mfma_f32_16x16x32_bf16 v[80:83], v[190:193], v[222:225], v[80:83]
	v_mfma_f32_16x16x32_bf16 v[72:75], v[168:171], v[230:233], v[72:75]
	v_mfma_f32_16x16x32_bf16 v[68:71], v[190:193], v[230:233], v[68:71]
	v_mfma_f32_16x16x32_bf16 v[56:59], v[168:171], v[246:249], v[56:59]
	v_mfma_f32_16x16x32_bf16 v[48:51], v[190:193], v[246:249], v[48:51]
	s_setprio 0
	s_setprio 1
	v_mfma_f32_16x16x32_bf16 v[28:31], v[194:197], v[210:213], v[28:31]
	v_mfma_f32_16x16x32_bf16 v[24:27], v[202:205], v[210:213], v[24:27]
	v_mfma_f32_16x16x32_bf16 v[20:23], v[194:197], v[218:221], v[20:23]
	v_mfma_f32_16x16x32_bf16 v[16:19], v[202:205], v[218:221], v[16:19]
	v_mfma_f32_16x16x32_bf16 v[12:15], v[194:197], v[226:229], v[12:15]
	v_mfma_f32_16x16x32_bf16 v[8:11], v[202:205], v[226:229], v[8:11]
	v_mfma_f32_16x16x32_bf16 v[4:7], v[194:197], v[242:245], v[4:7]
	v_mfma_f32_16x16x32_bf16 v[0:3], v[202:205], v[242:245], v[0:3]
	v_mfma_f32_16x16x32_bf16 v[28:31], v[198:201], v[214:217], v[28:31]
	v_mfma_f32_16x16x32_bf16 v[24:27], v[206:209], v[214:217], v[24:27]
	v_mfma_f32_16x16x32_bf16 v[20:23], v[198:201], v[222:225], v[20:23]
	v_mfma_f32_16x16x32_bf16 v[16:19], v[206:209], v[222:225], v[16:19]
	v_mfma_f32_16x16x32_bf16 v[12:15], v[198:201], v[230:233], v[12:15]
	v_mfma_f32_16x16x32_bf16 v[8:11], v[206:209], v[230:233], v[8:11]
	v_mfma_f32_16x16x32_bf16 v[4:7], v[198:201], v[246:249], v[4:7]
	v_mfma_f32_16x16x32_bf16 v[0:3], v[206:209], v[246:249], v[0:3]
	s_setprio 2
	s_barrier
	s_add_i32 s61, s61, 2
	s_add_u32 s30, s30, 0x100
	s_addc_u32 s31, s31, 0
	s_add_u32 s59, s59, 0x100
	s_addc_u32 s60, s60, 0
	s_cmp_gt_u32 s61, 13
	s_cbranch_scc0 .LBB0_361
	s_and_b64 vcc, exec, s[20:21]
	s_cbranch_vccz .LBB0_364
	s_barrier

.LBB0_393:
	s_add_u32 s26, s14, 0xfffc0080
	s_addc_u32 s27, s15, -1
	s_add_i32 s57, 0, 0x10000
	s_cmp_eq_u32 s56, 12
	s_cselect_b32 s29, s19, s27
	s_cselect_b32 s28, s52, s26
	v_add_u32_e32 v151, s57, v141
	s_cselect_b32 s27, s5, s55
	s_cselect_b32 s26, s53, s54
	s_add_i32 s60, 0, 0x14000
	ds_read_b128 v[162:165], v151
	ds_read_b128 v[166:169], v151 offset:1024
	ds_read_b128 v[170:173], v151 offset:2048
	ds_read_b128 v[186:189], v151 offset:3072
	v_add_u32_e32 v151, s60, v141
	ds_read_b128 v[190:193], v151
	ds_read_b128 v[194:197], v151 offset:1024
	ds_read_b128 v[198:201], v151 offset:2048
	ds_read_b128 v[202:205], v151 offset:3072
	v_lshl_add_u64 v[152:153], s[14:15], 0, v[146:147]
	s_add_i32 m0, s39, 0xc000
	ds_read_b128 v[206:209], v150
	ds_read_b128 v[210:213], v150 offset:1024
	ds_read_b128 v[214:217], v150 offset:2048
	ds_read_b128 v[218:221], v150 offset:3072
	ds_read_b128 v[222:225], v150 offset:4096
	ds_read_b128 v[226:229], v150 offset:5120
	ds_read_b128 v[230:233], v150 offset:6144
	ds_read_b128 v[242:245], v150 offset:7168
	global_load_lds_dwordx4 v[152:153], off
	v_lshl_add_u64 v[152:153], s[14:15], 0, v[148:149]
	s_add_i32 m0, s39, 0xe000
	s_nop 0
	global_load_lds_dwordx4 v[152:153], off
	s_setprio 1
	s_waitcnt vmcnt(8) lgkmcnt(0)
	s_barrier
	v_mfma_f32_16x16x32_bf16 v[126:129], v[162:165], v[206:209], v[126:129]
	v_mfma_f32_16x16x32_bf16 v[122:125], v[170:173], v[206:209], v[122:125]
	v_mfma_f32_16x16x32_bf16 v[118:121], v[162:165], v[214:217], v[118:121]
	v_mfma_f32_16x16x32_bf16 v[114:117], v[170:173], v[214:217], v[114:117]
	v_mfma_f32_16x16x32_bf16 v[110:113], v[162:165], v[222:225], v[110:113]
	v_mfma_f32_16x16x32_bf16 v[106:109], v[170:173], v[222:225], v[106:109]
	v_mfma_f32_16x16x32_bf16 v[102:105], v[162:165], v[230:233], v[102:105]
	v_mfma_f32_16x16x32_bf16 v[98:101], v[170:173], v[230:233], v[98:101]
	v_mfma_f32_16x16x32_bf16 v[126:129], v[166:169], v[210:213], v[126:129]
	v_mfma_f32_16x16x32_bf16 v[122:125], v[186:189], v[210:213], v[122:125]
	v_mfma_f32_16x16x32_bf16 v[118:121], v[166:169], v[218:221], v[118:121]
	v_mfma_f32_16x16x32_bf16 v[114:117], v[186:189], v[218:221], v[114:117]
	v_mfma_f32_16x16x32_bf16 v[110:113], v[166:169], v[226:229], v[110:113]
	v_mfma_f32_16x16x32_bf16 v[106:109], v[186:189], v[226:229], v[106:109]
	v_mfma_f32_16x16x32_bf16 v[102:105], v[166:169], v[242:245], v[102:105]
	v_mfma_f32_16x16x32_bf16 v[98:101], v[186:189], v[242:245], v[98:101]
	s_setprio 0
	s_setprio 1
	v_mfma_f32_16x16x32_bf16 v[68:71], v[190:193], v[206:209], v[68:71]
	v_mfma_f32_16x16x32_bf16 v[64:67], v[198:201], v[206:209], v[64:67]
	v_mfma_f32_16x16x32_bf16 v[52:55], v[190:193], v[214:217], v[52:55]
	v_mfma_f32_16x16x32_bf16 v[48:51], v[198:201], v[214:217], v[48:51]
	v_mfma_f32_16x16x32_bf16 v[44:47], v[190:193], v[222:225], v[44:47]
	v_mfma_f32_16x16x32_bf16 v[40:43], v[198:201], v[222:225], v[40:43]
	v_mfma_f32_16x16x32_bf16 v[36:39], v[190:193], v[230:233], v[36:39]
	v_mfma_f32_16x16x32_bf16 v[32:35], v[198:201], v[230:233], v[32:35]
	v_mfma_f32_16x16x32_bf16 v[68:71], v[194:197], v[210:213], v[68:71]
	v_mfma_f32_16x16x32_bf16 v[64:67], v[202:205], v[210:213], v[64:67]
	v_mfma_f32_16x16x32_bf16 v[52:55], v[194:197], v[218:221], v[52:55]
	v_mfma_f32_16x16x32_bf16 v[48:51], v[202:205], v[218:221], v[48:51]
	v_mfma_f32_16x16x32_bf16 v[44:47], v[194:197], v[226:229], v[44:47]
	v_mfma_f32_16x16x32_bf16 v[40:43], v[202:205], v[226:229], v[40:43]
	v_mfma_f32_16x16x32_bf16 v[36:39], v[194:197], v[242:245], v[36:39]
	v_mfma_f32_16x16x32_bf16 v[32:35], v[202:205], v[242:245], v[32:35]
	s_setprio 2
	s_barrier
	s_add_i32 s57, s57, s36
	v_lshl_add_u64 v[152:153], s[26:27], 0, v[96:97]
	s_mov_b32 m0, s57
	ds_read_b128 v[206:209], v150 offset:16384
	ds_read_b128 v[210:213], v150 offset:17408
	ds_read_b128 v[214:217], v150 offset:18432
	ds_read_b128 v[218:221], v150 offset:19456
	ds_read_b128 v[222:225], v150 offset:20480
	ds_read_b128 v[226:229], v150 offset:21504
	ds_read_b128 v[230:233], v150 offset:22528
	ds_read_b128 v[242:245], v150 offset:23552
	global_load_lds_dwordx4 v[152:153], off
	s_add_i32 m0, s57, 0x2000
	s_add_u32 s58, s26, 0x40000
	v_lshl_add_u64 v[154:155], s[26:27], 0, v[130:131]
	s_addc_u32 s59, s27, 0
	s_add_i32 s57, s60, s36
	global_load_lds_dwordx4 v[154:155], off
	v_lshl_add_u64 v[156:157], s[58:59], 0, v[96:97]
	s_mov_b32 m0, s57
	v_lshl_add_u64 v[158:159], s[28:29], 0, v[132:133]
	global_load_lds_dwordx4 v[156:157], off
	v_lshl_add_u64 v[156:157], s[58:59], 0, v[130:131]
	s_add_i32 m0, s57, 0x2000
	s_nop 0
	global_load_lds_dwordx4 v[156:157], off
	v_lshl_add_u64 v[156:157], s[28:29], 0, v[134:135]
	s_mov_b32 m0, s39
	s_nop 0
	global_load_lds_dwordx4 v[156:157], off
	s_mov_b32 m0, s40
	s_nop 0
	global_load_lds_dwordx4 v[158:159], off
	s_setprio 1
	s_waitcnt vmcnt(8) lgkmcnt(0)
	s_barrier
	v_mfma_f32_16x16x32_bf16 v[92:95], v[162:165], v[206:209], v[92:95]
	v_mfma_f32_16x16x32_bf16 v[88:91], v[170:173], v[206:209], v[88:91]
	v_mfma_f32_16x16x32_bf16 v[84:87], v[162:165], v[214:217], v[84:87]
	v_mfma_f32_16x16x32_bf16 v[80:83], v[170:173], v[214:217], v[80:83]
	v_mfma_f32_16x16x32_bf16 v[76:79], v[162:165], v[222:225], v[76:79]
	v_mfma_f32_16x16x32_bf16 v[72:75], v[170:173], v[222:225], v[72:75]
	v_mfma_f32_16x16x32_bf16 v[60:63], v[162:165], v[230:233], v[60:63]
	v_mfma_f32_16x16x32_bf16 v[56:59], v[170:173], v[230:233], v[56:59]
	v_mfma_f32_16x16x32_bf16 v[92:95], v[166:169], v[210:213], v[92:95]
	v_mfma_f32_16x16x32_bf16 v[88:91], v[186:189], v[210:213], v[88:91]
	v_mfma_f32_16x16x32_bf16 v[84:87], v[166:169], v[218:221], v[84:87]
	v_mfma_f32_16x16x32_bf16 v[80:83], v[186:189], v[218:221], v[80:83]
	v_mfma_f32_16x16x32_bf16 v[76:79], v[166:169], v[226:229], v[76:79]
	v_mfma_f32_16x16x32_bf16 v[72:75], v[186:189], v[226:229], v[72:75]
	v_mfma_f32_16x16x32_bf16 v[60:63], v[166:169], v[242:245], v[60:63]
	v_mfma_f32_16x16x32_bf16 v[56:59], v[186:189], v[242:245], v[56:59]
	s_setprio 0
	s_setprio 1
	v_mfma_f32_16x16x32_bf16 v[28:31], v[190:193], v[206:209], v[28:31]
	v_mfma_f32_16x16x32_bf16 v[24:27], v[198:201], v[206:209], v[24:27]
	v_mfma_f32_16x16x32_bf16 v[20:23], v[190:193], v[214:217], v[20:23]
	v_mfma_f32_16x16x32_bf16 v[16:19], v[198:201], v[214:217], v[16:19]
	v_mfma_f32_16x16x32_bf16 v[12:15], v[190:193], v[222:225], v[12:15]
	v_mfma_f32_16x16x32_bf16 v[8:11], v[198:201], v[222:225], v[8:11]
	v_mfma_f32_16x16x32_bf16 v[4:7], v[190:193], v[230:233], v[4:7]
	v_mfma_f32_16x16x32_bf16 v[0:3], v[198:201], v[230:233], v[0:3]
	v_mfma_f32_16x16x32_bf16 v[28:31], v[194:197], v[210:213], v[28:31]
	v_mfma_f32_16x16x32_bf16 v[24:27], v[202:205], v[210:213], v[24:27]
	v_mfma_f32_16x16x32_bf16 v[20:23], v[194:197], v[218:221], v[20:23]
	v_mfma_f32_16x16x32_bf16 v[16:19], v[202:205], v[218:221], v[16:19]
	v_mfma_f32_16x16x32_bf16 v[12:15], v[194:197], v[226:229], v[12:15]
	v_mfma_f32_16x16x32_bf16 v[8:11], v[202:205], v[226:229], v[8:11]
	v_mfma_f32_16x16x32_bf16 v[4:7], v[194:197], v[242:245], v[4:7]
	v_mfma_f32_16x16x32_bf16 v[0:3], v[202:205], v[242:245], v[0:3]
	s_setprio 2
	s_barrier
	s_add_i32 s57, 0, 0x18000
	v_add_u32_e32 v151, s57, v141
	s_add_i32 s58, 0, 0x1c000
	ds_read_b128 v[162:165], v151
	ds_read_b128 v[166:169], v151 offset:1024
	ds_read_b128 v[170:173], v151 offset:2048
	ds_read_b128 v[186:189], v151 offset:3072
	v_add_u32_e32 v151, s58, v141
	ds_read_b128 v[190:193], v151
	ds_read_b128 v[194:197], v151 offset:1024
	ds_read_b128 v[198:201], v151 offset:2048
	ds_read_b128 v[202:205], v151 offset:3072
	s_add_u32 s28, s28, 0x40000
	s_addc_u32 s29, s29, 0
	s_mov_b32 m0, s41
	v_lshl_add_u64 v[182:183], s[28:29], 0, v[134:135]
	ds_read_b128 v[206:209], v150 offset:32768
	ds_read_b128 v[210:213], v150 offset:33792
	ds_read_b128 v[214:217], v150 offset:34816
	ds_read_b128 v[218:221], v150 offset:35840
	ds_read_b128 v[222:225], v150 offset:36864
	ds_read_b128 v[226:229], v150 offset:37888
	ds_read_b128 v[230:233], v150 offset:38912
	ds_read_b128 v[242:245], v150 offset:39936
	global_load_lds_dwordx4 v[182:183], off
	v_lshl_add_u64 v[182:183], s[28:29], 0, v[132:133]
	s_mov_b32 m0, s42
	s_nop 0
	global_load_lds_dwordx4 v[182:183], off
	s_setprio 1
	s_waitcnt vmcnt(8) lgkmcnt(0)
	s_barrier
	v_mfma_f32_16x16x32_bf16 v[126:129], v[162:165], v[206:209], v[126:129]
	v_mfma_f32_16x16x32_bf16 v[122:125], v[170:173], v[206:209], v[122:125]
	v_mfma_f32_16x16x32_bf16 v[118:121], v[162:165], v[214:217], v[118:121]
	v_mfma_f32_16x16x32_bf16 v[114:117], v[170:173], v[214:217], v[114:117]
	v_mfma_f32_16x16x32_bf16 v[110:113], v[162:165], v[222:225], v[110:113]
	v_mfma_f32_16x16x32_bf16 v[106:109], v[170:173], v[222:225], v[106:109]
	v_mfma_f32_16x16x32_bf16 v[102:105], v[162:165], v[230:233], v[102:105]
	v_mfma_f32_16x16x32_bf16 v[98:101], v[170:173], v[230:233], v[98:101]
	v_mfma_f32_16x16x32_bf16 v[126:129], v[166:169], v[210:213], v[126:129]
	v_mfma_f32_16x16x32_bf16 v[122:125], v[186:189], v[210:213], v[122:125]
	v_mfma_f32_16x16x32_bf16 v[118:121], v[166:169], v[218:221], v[118:121]
	v_mfma_f32_16x16x32_bf16 v[114:117], v[186:189], v[218:221], v[114:117]
	v_mfma_f32_16x16x32_bf16 v[110:113], v[166:169], v[226:229], v[110:113]
	v_mfma_f32_16x16x32_bf16 v[106:109], v[186:189], v[226:229], v[106:109]
	v_mfma_f32_16x16x32_bf16 v[102:105], v[166:169], v[242:245], v[102:105]
	v_mfma_f32_16x16x32_bf16 v[98:101], v[186:189], v[242:245], v[98:101]
	s_setprio 0
	s_setprio 1
	v_mfma_f32_16x16x32_bf16 v[68:71], v[190:193], v[206:209], v[68:71]
	v_mfma_f32_16x16x32_bf16 v[64:67], v[198:201], v[206:209], v[64:67]
	v_mfma_f32_16x16x32_bf16 v[52:55], v[190:193], v[214:217], v[52:55]
	v_mfma_f32_16x16x32_bf16 v[48:51], v[198:201], v[214:217], v[48:51]
	v_mfma_f32_16x16x32_bf16 v[44:47], v[190:193], v[222:225], v[44:47]
	v_mfma_f32_16x16x32_bf16 v[40:43], v[198:201], v[222:225], v[40:43]
	v_mfma_f32_16x16x32_bf16 v[36:39], v[190:193], v[230:233], v[36:39]
	v_mfma_f32_16x16x32_bf16 v[32:35], v[198:201], v[230:233], v[32:35]
	v_mfma_f32_16x16x32_bf16 v[68:71], v[194:197], v[210:213], v[68:71]
	v_mfma_f32_16x16x32_bf16 v[64:67], v[202:205], v[210:213], v[64:67]
	v_mfma_f32_16x16x32_bf16 v[52:55], v[194:197], v[218:221], v[52:55]
	v_mfma_f32_16x16x32_bf16 v[48:51], v[202:205], v[218:221], v[48:51]
	v_mfma_f32_16x16x32_bf16 v[44:47], v[194:197], v[226:229], v[44:47]
	v_mfma_f32_16x16x32_bf16 v[40:43], v[202:205], v[226:229], v[40:43]
	v_mfma_f32_16x16x32_bf16 v[36:39], v[194:197], v[242:245], v[36:39]
	v_mfma_f32_16x16x32_bf16 v[32:35], v[202:205], v[242:245], v[32:35]
	s_setprio 2
	s_barrier
	s_add_i32 s28, s57, s36
	v_lshl_add_u64 v[152:153], v[152:153], 0, s[16:17]
	s_mov_b32 m0, s28
	ds_read_b128 v[206:209], v150 offset:49152
	ds_read_b128 v[210:213], v150 offset:50176
	ds_read_b128 v[214:217], v150 offset:51200
	ds_read_b128 v[218:221], v150 offset:52224
	ds_read_b128 v[222:225], v150 offset:53248
	ds_read_b128 v[226:229], v150 offset:54272
	ds_read_b128 v[230:233], v150 offset:55296
	ds_read_b128 v[242:245], v150 offset:56320
	global_load_lds_dwordx4 v[152:153], off
	s_add_i32 m0, s28, 0x2000
	s_add_u32 s26, s26, 0x40080
	v_lshl_add_u64 v[152:153], v[154:155], 0, s[16:17]
	s_addc_u32 s27, s27, 0
	s_add_i32 s28, s58, s36
	global_load_lds_dwordx4 v[152:153], off
	v_lshl_add_u64 v[152:153], s[26:27], 0, v[96:97]
	s_mov_b32 m0, s28
	s_nop 0
	global_load_lds_dwordx4 v[152:153], off
	v_lshl_add_u64 v[152:153], s[26:27], 0, v[130:131]
	s_add_i32 m0, s28, 0x2000
	s_nop 0
	global_load_lds_dwordx4 v[152:153], off
	v_lshl_add_u64 v[152:153], v[156:157], 0, s[16:17]
	s_mov_b32 m0, s45
	s_nop 0
	global_load_lds_dwordx4 v[152:153], off
	v_lshl_add_u64 v[152:153], v[158:159], 0, s[16:17]
	s_mov_b32 m0, s46
	s_nop 0
	global_load_lds_dwordx4 v[152:153], off
	s_setprio 1
	s_waitcnt vmcnt(8) lgkmcnt(0)
	s_barrier
	v_mfma_f32_16x16x32_bf16 v[92:95], v[162:165], v[206:209], v[92:95]
	v_mfma_f32_16x16x32_bf16 v[88:91], v[170:173], v[206:209], v[88:91]
	v_mfma_f32_16x16x32_bf16 v[84:87], v[162:165], v[214:217], v[84:87]
	v_mfma_f32_16x16x32_bf16 v[80:83], v[170:173], v[214:217], v[80:83]
	v_mfma_f32_16x16x32_bf16 v[76:79], v[162:165], v[222:225], v[76:79]
	v_mfma_f32_16x16x32_bf16 v[72:75], v[170:173], v[222:225], v[72:75]
	v_mfma_f32_16x16x32_bf16 v[60:63], v[162:165], v[230:233], v[60:63]
	v_mfma_f32_16x16x32_bf16 v[56:59], v[170:173], v[230:233], v[56:59]
	v_mfma_f32_16x16x32_bf16 v[92:95], v[166:169], v[210:213], v[92:95]
	v_mfma_f32_16x16x32_bf16 v[88:91], v[186:189], v[210:213], v[88:91]
	v_mfma_f32_16x16x32_bf16 v[84:87], v[166:169], v[218:221], v[84:87]
	v_mfma_f32_16x16x32_bf16 v[80:83], v[186:189], v[218:221], v[80:83]
	v_mfma_f32_16x16x32_bf16 v[76:79], v[166:169], v[226:229], v[76:79]
	v_mfma_f32_16x16x32_bf16 v[72:75], v[186:189], v[226:229], v[72:75]
	v_mfma_f32_16x16x32_bf16 v[60:63], v[166:169], v[242:245], v[60:63]
	v_mfma_f32_16x16x32_bf16 v[56:59], v[186:189], v[242:245], v[56:59]
	s_setprio 0
	s_setprio 1
	v_mfma_f32_16x16x32_bf16 v[28:31], v[190:193], v[206:209], v[28:31]
	v_mfma_f32_16x16x32_bf16 v[24:27], v[198:201], v[206:209], v[24:27]
	v_mfma_f32_16x16x32_bf16 v[20:23], v[190:193], v[214:217], v[20:23]
	v_mfma_f32_16x16x32_bf16 v[16:19], v[198:201], v[214:217], v[16:19]
	v_mfma_f32_16x16x32_bf16 v[12:15], v[190:193], v[222:225], v[12:15]
	v_mfma_f32_16x16x32_bf16 v[8:11], v[198:201], v[222:225], v[8:11]
	v_mfma_f32_16x16x32_bf16 v[4:7], v[190:193], v[230:233], v[4:7]
	v_mfma_f32_16x16x32_bf16 v[0:3], v[198:201], v[230:233], v[0:3]
	v_mfma_f32_16x16x32_bf16 v[28:31], v[194:197], v[210:213], v[28:31]
	v_mfma_f32_16x16x32_bf16 v[24:27], v[202:205], v[210:213], v[24:27]
	v_mfma_f32_16x16x32_bf16 v[20:23], v[194:197], v[218:221], v[20:23]
	v_mfma_f32_16x16x32_bf16 v[16:19], v[202:205], v[218:221], v[16:19]
	v_mfma_f32_16x16x32_bf16 v[12:15], v[194:197], v[226:229], v[12:15]
	v_mfma_f32_16x16x32_bf16 v[8:11], v[202:205], v[226:229], v[8:11]
	v_mfma_f32_16x16x32_bf16 v[4:7], v[194:197], v[242:245], v[4:7]
	v_mfma_f32_16x16x32_bf16 v[0:3], v[202:205], v[242:245], v[0:3]
	s_setprio 2
	s_barrier
	s_add_i32 s56, s56, 2
	s_add_u32 s14, s14, 0x100
	s_addc_u32 s15, s15, 0
	s_add_u32 s54, s54, 0x100
	s_addc_u32 s55, s55, 0
	s_cmp_gt_u32 s56, 13
	s_cbranch_scc0 .LBB0_393
	s_and_b64 vcc, exec, s[12:13]
	s_cbranch_vccz .LBB0_396
	s_barrier

.LBB0_427:
	s_add_u32 s14, s4, 0xfffc0080
	s_addc_u32 s15, s5, -1
	s_add_i32 s62, 0, 0x10000
	s_cmp_eq_u32 s61, 12
	s_cselect_b32 s37, s29, s15
	s_cselect_b32 s36, s57, s14
	v_add_u32_e32 v154, s62, v169
	s_cselect_b32 s15, s27, s60
	s_cselect_b32 s14, s58, s59
	s_add_i32 s64, 0, 0x14000
	ds_read_b128 v[142:145], v154
	ds_read_b128 v[146:149], v154 offset:1024
	ds_read_b128 v[150:153], v154 offset:2048
	ds_read_b128 v[162:165], v154 offset:3072
	v_add_u32_e32 v154, s64, v169
	ds_read_b128 v[186:189], v154
	ds_read_b128 v[190:193], v154 offset:1024
	ds_read_b128 v[194:197], v154 offset:2048
	ds_read_b128 v[198:201], v154 offset:3072
	v_lshl_add_u64 v[154:155], s[4:5], 0, v[138:139]
	s_add_i32 m0, s43, 0xc000
	ds_read_b128 v[202:205], v173
	ds_read_b128 v[206:209], v173 offset:1024
	ds_read_b128 v[210:213], v173 offset:2048
	ds_read_b128 v[214:217], v173 offset:3072
	ds_read_b128 v[218:221], v173 offset:4096
	ds_read_b128 v[222:225], v173 offset:5120
	ds_read_b128 v[226:229], v173 offset:6144
	ds_read_b128 v[230:233], v173 offset:7168
	global_load_lds_dwordx4 v[154:155], off
	v_lshl_add_u64 v[154:155], s[4:5], 0, v[140:141]
	s_add_i32 m0, s43, 0xe000
	s_nop 0
	global_load_lds_dwordx4 v[154:155], off
	s_setprio 1
	s_waitcnt vmcnt(8) lgkmcnt(0)
	s_barrier
	v_mfma_f32_16x16x32_bf16 v[126:129], v[142:145], v[202:205], v[126:129]
	v_mfma_f32_16x16x32_bf16 v[122:125], v[150:153], v[202:205], v[122:125]
	v_mfma_f32_16x16x32_bf16 v[110:113], v[142:145], v[210:213], v[110:113]
	v_mfma_f32_16x16x32_bf16 v[106:109], v[150:153], v[210:213], v[106:109]
	v_mfma_f32_16x16x32_bf16 v[92:95], v[142:145], v[218:221], v[92:95]
	v_mfma_f32_16x16x32_bf16 v[88:91], v[150:153], v[218:221], v[88:91]
	v_mfma_f32_16x16x32_bf16 v[76:79], v[142:145], v[226:229], v[76:79]
	v_mfma_f32_16x16x32_bf16 v[72:75], v[150:153], v[226:229], v[72:75]
	v_mfma_f32_16x16x32_bf16 v[126:129], v[146:149], v[206:209], v[126:129]
	v_mfma_f32_16x16x32_bf16 v[122:125], v[162:165], v[206:209], v[122:125]
	v_mfma_f32_16x16x32_bf16 v[110:113], v[146:149], v[214:217], v[110:113]
	v_mfma_f32_16x16x32_bf16 v[106:109], v[162:165], v[214:217], v[106:109]
	v_mfma_f32_16x16x32_bf16 v[92:95], v[146:149], v[222:225], v[92:95]
	v_mfma_f32_16x16x32_bf16 v[88:91], v[162:165], v[222:225], v[88:91]
	v_mfma_f32_16x16x32_bf16 v[76:79], v[146:149], v[230:233], v[76:79]
	v_mfma_f32_16x16x32_bf16 v[72:75], v[162:165], v[230:233], v[72:75]
	s_setprio 0
	s_setprio 1
	v_mfma_f32_16x16x32_bf16 v[118:121], v[186:189], v[202:205], v[118:121]
	v_mfma_f32_16x16x32_bf16 v[114:117], v[194:197], v[202:205], v[114:117]
	v_mfma_f32_16x16x32_bf16 v[102:105], v[186:189], v[210:213], v[102:105]
	v_mfma_f32_16x16x32_bf16 v[98:101], v[194:197], v[210:213], v[98:101]
	v_mfma_f32_16x16x32_bf16 v[84:87], v[186:189], v[218:221], v[84:87]
	v_mfma_f32_16x16x32_bf16 v[80:83], v[194:197], v[218:221], v[80:83]
	v_mfma_f32_16x16x32_bf16 v[68:71], v[186:189], v[226:229], v[68:71]
	v_mfma_f32_16x16x32_bf16 v[64:67], v[194:197], v[226:229], v[64:67]
	v_mfma_f32_16x16x32_bf16 v[118:121], v[190:193], v[206:209], v[118:121]
	v_mfma_f32_16x16x32_bf16 v[114:117], v[198:201], v[206:209], v[114:117]
	v_mfma_f32_16x16x32_bf16 v[102:105], v[190:193], v[214:217], v[102:105]
	v_mfma_f32_16x16x32_bf16 v[98:101], v[198:201], v[214:217], v[98:101]
	v_mfma_f32_16x16x32_bf16 v[84:87], v[190:193], v[222:225], v[84:87]
	v_mfma_f32_16x16x32_bf16 v[80:83], v[198:201], v[222:225], v[80:83]
	v_mfma_f32_16x16x32_bf16 v[68:71], v[190:193], v[230:233], v[68:71]
	v_mfma_f32_16x16x32_bf16 v[64:67], v[198:201], v[230:233], v[64:67]
	s_setprio 2
	s_barrier
	s_add_i32 s62, s62, s42
	v_lshl_add_u64 v[154:155], s[14:15], 0, v[96:97]
	s_mov_b32 m0, s62
	ds_read_b128 v[202:205], v173 offset:16384
	ds_read_b128 v[206:209], v173 offset:17408
	ds_read_b128 v[210:213], v173 offset:18432
	ds_read_b128 v[214:217], v173 offset:19456
	ds_read_b128 v[218:221], v173 offset:20480
	ds_read_b128 v[222:225], v173 offset:21504
	ds_read_b128 v[226:229], v173 offset:22528
	ds_read_b128 v[230:233], v173 offset:23552
	global_load_lds_dwordx4 v[154:155], off
	s_add_i32 m0, s62, 0x2000
	s_add_u32 s62, s14, 0x40000
	v_lshl_add_u64 v[156:157], s[14:15], 0, v[130:131]
	s_addc_u32 s63, s15, 0
	s_add_i32 s64, s64, s42
	global_load_lds_dwordx4 v[156:157], off
	v_lshl_add_u64 v[158:159], s[62:63], 0, v[96:97]
	s_mov_b32 m0, s64
	v_lshl_add_u64 v[166:167], s[36:37], 0, v[132:133]
	global_load_lds_dwordx4 v[158:159], off
	v_lshl_add_u64 v[158:159], s[62:63], 0, v[130:131]
	s_add_i32 m0, s64, 0x2000
	s_nop 0
	global_load_lds_dwordx4 v[158:159], off
	v_lshl_add_u64 v[158:159], s[36:37], 0, v[134:135]
	s_mov_b32 m0, s43
	s_nop 0
	global_load_lds_dwordx4 v[158:159], off
	s_mov_b32 m0, s44
	s_nop 0
	global_load_lds_dwordx4 v[166:167], off
	s_setprio 1
	s_waitcnt vmcnt(8) lgkmcnt(0)
	s_barrier
	v_mfma_f32_16x16x32_bf16 v[60:63], v[142:145], v[202:205], v[60:63]
	v_mfma_f32_16x16x32_bf16 v[56:59], v[150:153], v[202:205], v[56:59]
	v_mfma_f32_16x16x32_bf16 v[44:47], v[142:145], v[210:213], v[44:47]
	v_mfma_f32_16x16x32_bf16 v[40:43], v[150:153], v[210:213], v[40:43]
	v_mfma_f32_16x16x32_bf16 v[28:31], v[142:145], v[218:221], v[28:31]
	v_mfma_f32_16x16x32_bf16 v[24:27], v[150:153], v[218:221], v[24:27]
	v_mfma_f32_16x16x32_bf16 v[12:15], v[142:145], v[226:229], v[12:15]
	v_mfma_f32_16x16x32_bf16 v[8:11], v[150:153], v[226:229], v[8:11]
	v_mfma_f32_16x16x32_bf16 v[60:63], v[146:149], v[206:209], v[60:63]
	v_mfma_f32_16x16x32_bf16 v[56:59], v[162:165], v[206:209], v[56:59]
	v_mfma_f32_16x16x32_bf16 v[44:47], v[146:149], v[214:217], v[44:47]
	v_mfma_f32_16x16x32_bf16 v[40:43], v[162:165], v[214:217], v[40:43]
	v_mfma_f32_16x16x32_bf16 v[28:31], v[146:149], v[222:225], v[28:31]
	v_mfma_f32_16x16x32_bf16 v[24:27], v[162:165], v[222:225], v[24:27]
	v_mfma_f32_16x16x32_bf16 v[12:15], v[146:149], v[230:233], v[12:15]
	v_mfma_f32_16x16x32_bf16 v[8:11], v[162:165], v[230:233], v[8:11]
	s_setprio 0
	s_setprio 1
	v_mfma_f32_16x16x32_bf16 v[52:55], v[186:189], v[202:205], v[52:55]
	v_mfma_f32_16x16x32_bf16 v[48:51], v[194:197], v[202:205], v[48:51]
	v_mfma_f32_16x16x32_bf16 v[36:39], v[186:189], v[210:213], v[36:39]
	v_mfma_f32_16x16x32_bf16 v[32:35], v[194:197], v[210:213], v[32:35]
	v_mfma_f32_16x16x32_bf16 v[20:23], v[186:189], v[218:221], v[20:23]
	v_mfma_f32_16x16x32_bf16 v[16:19], v[194:197], v[218:221], v[16:19]
	v_mfma_f32_16x16x32_bf16 v[4:7], v[186:189], v[226:229], v[4:7]
	v_mfma_f32_16x16x32_bf16 v[0:3], v[194:197], v[226:229], v[0:3]
	v_mfma_f32_16x16x32_bf16 v[52:55], v[190:193], v[206:209], v[52:55]
	v_mfma_f32_16x16x32_bf16 v[48:51], v[198:201], v[206:209], v[48:51]
	v_mfma_f32_16x16x32_bf16 v[36:39], v[190:193], v[214:217], v[36:39]
	v_mfma_f32_16x16x32_bf16 v[32:35], v[198:201], v[214:217], v[32:35]
	v_mfma_f32_16x16x32_bf16 v[20:23], v[190:193], v[222:225], v[20:23]
	v_mfma_f32_16x16x32_bf16 v[16:19], v[198:201], v[222:225], v[16:19]
	v_mfma_f32_16x16x32_bf16 v[4:7], v[190:193], v[230:233], v[4:7]
	v_mfma_f32_16x16x32_bf16 v[0:3], v[198:201], v[230:233], v[0:3]
	s_setprio 2
	s_barrier
	s_add_i32 s62, 0, 0x18000
	s_add_i32 s63, 0, 0x1c000
	v_add_u32_e32 v162, s62, v169
	v_add_u32_e32 v182, s63, v169
	ds_read_b128 v[142:145], v162
	ds_read_b128 v[146:149], v162 offset:1024
	ds_read_b128 v[150:153], v162 offset:2048
	ds_read_b128 v[162:165], v162 offset:3072
	ds_read_b128 v[186:189], v182
	ds_read_b128 v[190:193], v182 offset:1024
	ds_read_b128 v[194:197], v182 offset:2048
	ds_read_b128 v[198:201], v182 offset:3072
	s_add_u32 s36, s36, 0x40000
	s_addc_u32 s37, s37, 0
	s_mov_b32 m0, s45
	v_lshl_add_u64 v[182:183], s[36:37], 0, v[134:135]
	ds_read_b128 v[202:205], v173 offset:32768
	ds_read_b128 v[206:209], v173 offset:33792
	ds_read_b128 v[210:213], v173 offset:34816
	ds_read_b128 v[214:217], v173 offset:35840
	ds_read_b128 v[218:221], v173 offset:36864
	ds_read_b128 v[222:225], v173 offset:37888
	ds_read_b128 v[226:229], v173 offset:38912
	ds_read_b128 v[230:233], v173 offset:39936
	global_load_lds_dwordx4 v[182:183], off
	v_lshl_add_u64 v[182:183], s[36:37], 0, v[132:133]
	s_mov_b32 m0, s46
	s_nop 0
	global_load_lds_dwordx4 v[182:183], off
	s_setprio 1
	s_waitcnt vmcnt(8) lgkmcnt(0)
	s_barrier
	v_mfma_f32_16x16x32_bf16 v[126:129], v[142:145], v[202:205], v[126:129]
	v_mfma_f32_16x16x32_bf16 v[122:125], v[150:153], v[202:205], v[122:125]
	v_mfma_f32_16x16x32_bf16 v[110:113], v[142:145], v[210:213], v[110:113]
	v_mfma_f32_16x16x32_bf16 v[106:109], v[150:153], v[210:213], v[106:109]
	v_mfma_f32_16x16x32_bf16 v[92:95], v[142:145], v[218:221], v[92:95]
	v_mfma_f32_16x16x32_bf16 v[88:91], v[150:153], v[218:221], v[88:91]
	v_mfma_f32_16x16x32_bf16 v[76:79], v[142:145], v[226:229], v[76:79]
	v_mfma_f32_16x16x32_bf16 v[72:75], v[150:153], v[226:229], v[72:75]
	v_mfma_f32_16x16x32_bf16 v[126:129], v[146:149], v[206:209], v[126:129]
	v_mfma_f32_16x16x32_bf16 v[122:125], v[162:165], v[206:209], v[122:125]
	v_mfma_f32_16x16x32_bf16 v[110:113], v[146:149], v[214:217], v[110:113]
	v_mfma_f32_16x16x32_bf16 v[106:109], v[162:165], v[214:217], v[106:109]
	v_mfma_f32_16x16x32_bf16 v[92:95], v[146:149], v[222:225], v[92:95]
	v_mfma_f32_16x16x32_bf16 v[88:91], v[162:165], v[222:225], v[88:91]
	v_mfma_f32_16x16x32_bf16 v[76:79], v[146:149], v[230:233], v[76:79]
	v_mfma_f32_16x16x32_bf16 v[72:75], v[162:165], v[230:233], v[72:75]
	s_setprio 0
	s_setprio 1
	v_mfma_f32_16x16x32_bf16 v[118:121], v[186:189], v[202:205], v[118:121]
	v_mfma_f32_16x16x32_bf16 v[114:117], v[194:197], v[202:205], v[114:117]
	v_mfma_f32_16x16x32_bf16 v[102:105], v[186:189], v[210:213], v[102:105]
	v_mfma_f32_16x16x32_bf16 v[98:101], v[194:197], v[210:213], v[98:101]
	v_mfma_f32_16x16x32_bf16 v[84:87], v[186:189], v[218:221], v[84:87]
	v_mfma_f32_16x16x32_bf16 v[80:83], v[194:197], v[218:221], v[80:83]
	v_mfma_f32_16x16x32_bf16 v[68:71], v[186:189], v[226:229], v[68:71]
	v_mfma_f32_16x16x32_bf16 v[64:67], v[194:197], v[226:229], v[64:67]
	v_mfma_f32_16x16x32_bf16 v[118:121], v[190:193], v[206:209], v[118:121]
	v_mfma_f32_16x16x32_bf16 v[114:117], v[198:201], v[206:209], v[114:117]
	v_mfma_f32_16x16x32_bf16 v[102:105], v[190:193], v[214:217], v[102:105]
	v_mfma_f32_16x16x32_bf16 v[98:101], v[198:201], v[214:217], v[98:101]
	v_mfma_f32_16x16x32_bf16 v[84:87], v[190:193], v[222:225], v[84:87]
	v_mfma_f32_16x16x32_bf16 v[80:83], v[198:201], v[222:225], v[80:83]
	v_mfma_f32_16x16x32_bf16 v[68:71], v[190:193], v[230:233], v[68:71]
	v_mfma_f32_16x16x32_bf16 v[64:67], v[198:201], v[230:233], v[64:67]
	s_setprio 2
	s_barrier
	s_add_i32 s36, s62, s42
	v_lshl_add_u64 v[154:155], v[154:155], 0, s[16:17]
	s_mov_b32 m0, s36
	ds_read_b128 v[202:205], v173 offset:49152
	ds_read_b128 v[206:209], v173 offset:50176
	ds_read_b128 v[210:213], v173 offset:51200
	ds_read_b128 v[214:217], v173 offset:52224
	ds_read_b128 v[218:221], v173 offset:53248
	ds_read_b128 v[222:225], v173 offset:54272
	ds_read_b128 v[226:229], v173 offset:55296
	ds_read_b128 v[230:233], v173 offset:56320
	global_load_lds_dwordx4 v[154:155], off
	s_add_i32 m0, s36, 0x2000
	s_add_u32 s14, s14, 0x40080
	v_lshl_add_u64 v[154:155], v[156:157], 0, s[16:17]
	s_addc_u32 s15, s15, 0
	s_add_i32 s36, s63, s42
	global_load_lds_dwordx4 v[154:155], off
	v_lshl_add_u64 v[154:155], s[14:15], 0, v[96:97]
	s_mov_b32 m0, s36
	s_nop 0
	global_load_lds_dwordx4 v[154:155], off
	v_lshl_add_u64 v[154:155], s[14:15], 0, v[130:131]
	s_add_i32 m0, s36, 0x2000
	s_nop 0
	global_load_lds_dwordx4 v[154:155], off
	v_lshl_add_u64 v[154:155], v[158:159], 0, s[16:17]
	s_mov_b32 m0, s52
	s_nop 0
	global_load_lds_dwordx4 v[154:155], off
	v_lshl_add_u64 v[154:155], v[166:167], 0, s[16:17]
	s_mov_b32 m0, s53
	s_nop 0
	global_load_lds_dwordx4 v[154:155], off
	s_setprio 1
	s_waitcnt vmcnt(8) lgkmcnt(0)
	s_barrier
	v_mfma_f32_16x16x32_bf16 v[60:63], v[142:145], v[202:205], v[60:63]
	v_mfma_f32_16x16x32_bf16 v[56:59], v[150:153], v[202:205], v[56:59]
	v_mfma_f32_16x16x32_bf16 v[44:47], v[142:145], v[210:213], v[44:47]
	v_mfma_f32_16x16x32_bf16 v[40:43], v[150:153], v[210:213], v[40:43]
	v_mfma_f32_16x16x32_bf16 v[28:31], v[142:145], v[218:221], v[28:31]
	v_mfma_f32_16x16x32_bf16 v[24:27], v[150:153], v[218:221], v[24:27]
	v_mfma_f32_16x16x32_bf16 v[12:15], v[142:145], v[226:229], v[12:15]
	v_mfma_f32_16x16x32_bf16 v[8:11], v[150:153], v[226:229], v[8:11]
	v_mfma_f32_16x16x32_bf16 v[60:63], v[146:149], v[206:209], v[60:63]
	v_mfma_f32_16x16x32_bf16 v[56:59], v[162:165], v[206:209], v[56:59]
	v_mfma_f32_16x16x32_bf16 v[44:47], v[146:149], v[214:217], v[44:47]
	v_mfma_f32_16x16x32_bf16 v[40:43], v[162:165], v[214:217], v[40:43]
	v_mfma_f32_16x16x32_bf16 v[28:31], v[146:149], v[222:225], v[28:31]
	v_mfma_f32_16x16x32_bf16 v[24:27], v[162:165], v[222:225], v[24:27]
	v_mfma_f32_16x16x32_bf16 v[12:15], v[146:149], v[230:233], v[12:15]
	v_mfma_f32_16x16x32_bf16 v[8:11], v[162:165], v[230:233], v[8:11]
	s_setprio 0
	s_setprio 1
	v_mfma_f32_16x16x32_bf16 v[52:55], v[186:189], v[202:205], v[52:55]
	v_mfma_f32_16x16x32_bf16 v[48:51], v[194:197], v[202:205], v[48:51]
	v_mfma_f32_16x16x32_bf16 v[36:39], v[186:189], v[210:213], v[36:39]
	v_mfma_f32_16x16x32_bf16 v[32:35], v[194:197], v[210:213], v[32:35]
	v_mfma_f32_16x16x32_bf16 v[20:23], v[186:189], v[218:221], v[20:23]
	v_mfma_f32_16x16x32_bf16 v[16:19], v[194:197], v[218:221], v[16:19]
	v_mfma_f32_16x16x32_bf16 v[4:7], v[186:189], v[226:229], v[4:7]
	v_mfma_f32_16x16x32_bf16 v[0:3], v[194:197], v[226:229], v[0:3]
	v_mfma_f32_16x16x32_bf16 v[52:55], v[190:193], v[206:209], v[52:55]
	v_mfma_f32_16x16x32_bf16 v[48:51], v[198:201], v[206:209], v[48:51]
	v_mfma_f32_16x16x32_bf16 v[36:39], v[190:193], v[214:217], v[36:39]
	v_mfma_f32_16x16x32_bf16 v[32:35], v[198:201], v[214:217], v[32:35]
	v_mfma_f32_16x16x32_bf16 v[20:23], v[190:193], v[222:225], v[20:23]
	v_mfma_f32_16x16x32_bf16 v[16:19], v[198:201], v[222:225], v[16:19]
	v_mfma_f32_16x16x32_bf16 v[4:7], v[190:193], v[230:233], v[4:7]
	v_mfma_f32_16x16x32_bf16 v[0:3], v[198:201], v[230:233], v[0:3]
	s_setprio 2
	s_barrier
	s_add_i32 s61, s61, 2
	s_add_u32 s4, s4, 0x100
	s_addc_u32 s5, s5, 0
	s_add_u32 s59, s59, 0x100
	s_addc_u32 s60, s60, 0
	s_cmp_gt_u32 s61, 13
	s_cbranch_scc0 .LBB0_427
	s_and_b64 vcc, exec, s[24:25]
	s_cbranch_vccz .LBB0_430
	s_barrier

.LBB0_449:
	s_add_u32 s30, s14, 0xfffc0080
	s_addc_u32 s31, s15, -1
	s_add_i32 s60, 0, 0x10000
	s_cmp_eq_u32 s59, 12
	s_cselect_b32 s35, s25, s31
	s_cselect_b32 s34, s55, s30
	v_add_u32_e32 v96, s60, v151
	s_cselect_b32 s31, s13, s58
	s_cselect_b32 s30, s56, s57
	s_add_i32 s62, 0, 0x14000
	ds_read_b128 v[144:147], v96
	ds_read_b128 v[164:167], v96 offset:1024
	ds_read_b128 v[168:171], v96 offset:2048
	ds_read_b128 v[186:189], v96 offset:3072
	v_add_u32_e32 v96, s62, v151
	ds_read_b128 v[190:193], v96
	ds_read_b128 v[194:197], v96 offset:1024
	ds_read_b128 v[198:201], v96 offset:2048
	ds_read_b128 v[202:205], v96 offset:3072
	v_lshl_add_u64 v[148:149], s[14:15], 0, v[140:141]
	s_add_i32 m0, s41, 0xc000
	ds_read_b128 v[206:209], v163
	ds_read_b128 v[210:213], v163 offset:1024
	ds_read_b128 v[214:217], v163 offset:2048
	ds_read_b128 v[218:221], v163 offset:3072
	ds_read_b128 v[222:225], v163 offset:4096
	ds_read_b128 v[226:229], v163 offset:5120
	ds_read_b128 v[230:233], v163 offset:6144
	ds_read_b128 v[242:245], v163 offset:7168
	global_load_lds_dwordx4 v[148:149], off
	v_lshl_add_u64 v[148:149], s[14:15], 0, v[142:143]
	s_add_i32 m0, s41, 0xe000
	s_nop 0
	global_load_lds_dwordx4 v[148:149], off
	s_setprio 1
	s_waitcnt vmcnt(8) lgkmcnt(0)
	s_barrier
	v_mfma_f32_16x16x32_bf16 v[126:129], v[144:147], v[206:209], v[126:129]
	v_mfma_f32_16x16x32_bf16 v[122:125], v[168:171], v[206:209], v[122:125]
	v_mfma_f32_16x16x32_bf16 v[110:113], v[144:147], v[214:217], v[110:113]
	v_mfma_f32_16x16x32_bf16 v[106:109], v[168:171], v[214:217], v[106:109]
	v_mfma_f32_16x16x32_bf16 v[92:95], v[144:147], v[222:225], v[92:95]
	v_mfma_f32_16x16x32_bf16 v[88:91], v[168:171], v[222:225], v[88:91]
	v_mfma_f32_16x16x32_bf16 v[76:79], v[144:147], v[230:233], v[76:79]
	v_mfma_f32_16x16x32_bf16 v[72:75], v[168:171], v[230:233], v[72:75]
	v_mfma_f32_16x16x32_bf16 v[126:129], v[164:167], v[210:213], v[126:129]
	v_mfma_f32_16x16x32_bf16 v[122:125], v[186:189], v[210:213], v[122:125]
	v_mfma_f32_16x16x32_bf16 v[110:113], v[164:167], v[218:221], v[110:113]
	v_mfma_f32_16x16x32_bf16 v[106:109], v[186:189], v[218:221], v[106:109]
	v_mfma_f32_16x16x32_bf16 v[92:95], v[164:167], v[226:229], v[92:95]
	v_mfma_f32_16x16x32_bf16 v[88:91], v[186:189], v[226:229], v[88:91]
	v_mfma_f32_16x16x32_bf16 v[76:79], v[164:167], v[242:245], v[76:79]
	v_mfma_f32_16x16x32_bf16 v[72:75], v[186:189], v[242:245], v[72:75]
	s_setprio 0
	s_setprio 1
	v_mfma_f32_16x16x32_bf16 v[118:121], v[190:193], v[206:209], v[118:121]
	v_mfma_f32_16x16x32_bf16 v[114:117], v[198:201], v[206:209], v[114:117]
	v_mfma_f32_16x16x32_bf16 v[102:105], v[190:193], v[214:217], v[102:105]
	v_mfma_f32_16x16x32_bf16 v[98:101], v[198:201], v[214:217], v[98:101]
	v_mfma_f32_16x16x32_bf16 v[84:87], v[190:193], v[222:225], v[84:87]
	v_mfma_f32_16x16x32_bf16 v[80:83], v[198:201], v[222:225], v[80:83]
	v_mfma_f32_16x16x32_bf16 v[68:71], v[190:193], v[230:233], v[68:71]
	v_mfma_f32_16x16x32_bf16 v[64:67], v[198:201], v[230:233], v[64:67]
	v_mfma_f32_16x16x32_bf16 v[118:121], v[194:197], v[210:213], v[118:121]
	v_mfma_f32_16x16x32_bf16 v[114:117], v[202:205], v[210:213], v[114:117]
	v_mfma_f32_16x16x32_bf16 v[102:105], v[194:197], v[218:221], v[102:105]
	v_mfma_f32_16x16x32_bf16 v[98:101], v[202:205], v[218:221], v[98:101]
	v_mfma_f32_16x16x32_bf16 v[84:87], v[194:197], v[226:229], v[84:87]
	v_mfma_f32_16x16x32_bf16 v[80:83], v[202:205], v[226:229], v[80:83]
	v_mfma_f32_16x16x32_bf16 v[68:71], v[194:197], v[242:245], v[68:71]
	v_mfma_f32_16x16x32_bf16 v[64:67], v[202:205], v[242:245], v[64:67]
	s_setprio 2
	s_barrier
	s_add_i32 s60, s60, s40
	v_lshl_add_u64 v[148:149], s[30:31], 0, v[134:135]
	s_mov_b32 m0, s60
	ds_read_b128 v[206:209], v163 offset:16384
	ds_read_b128 v[210:213], v163 offset:17408
	ds_read_b128 v[214:217], v163 offset:18432
	ds_read_b128 v[218:221], v163 offset:19456
	ds_read_b128 v[222:225], v163 offset:20480
	ds_read_b128 v[226:229], v163 offset:21504
	ds_read_b128 v[230:233], v163 offset:22528
	ds_read_b128 v[242:245], v163 offset:23552
	global_load_lds_dwordx4 v[148:149], off
	s_add_i32 m0, s60, 0x2000
	s_add_u32 s60, s30, 0x40000
	v_lshl_add_u64 v[154:155], s[30:31], 0, v[130:131]
	s_addc_u32 s61, s31, 0
	s_add_i32 s62, s62, s40
	global_load_lds_dwordx4 v[154:155], off
	v_lshl_add_u64 v[156:157], s[60:61], 0, v[134:135]
	s_mov_b32 m0, s62
	v_lshl_add_u64 v[158:159], s[34:35], 0, v[132:133]
	global_load_lds_dwordx4 v[156:157], off
	v_lshl_add_u64 v[156:157], s[60:61], 0, v[130:131]
	s_add_i32 m0, s62, 0x2000
	s_nop 0
	global_load_lds_dwordx4 v[156:157], off
	v_lshl_add_u64 v[156:157], s[34:35], 0, v[136:137]
	s_mov_b32 m0, s41
	s_nop 0
	global_load_lds_dwordx4 v[156:157], off
	s_mov_b32 m0, s42
	s_nop 0
	global_load_lds_dwordx4 v[158:159], off
	s_setprio 1
	s_waitcnt vmcnt(8) lgkmcnt(0)
	s_barrier
	v_mfma_f32_16x16x32_bf16 v[60:63], v[144:147], v[206:209], v[60:63]
	v_mfma_f32_16x16x32_bf16 v[56:59], v[168:171], v[206:209], v[56:59]
	v_mfma_f32_16x16x32_bf16 v[44:47], v[144:147], v[214:217], v[44:47]
	v_mfma_f32_16x16x32_bf16 v[40:43], v[168:171], v[214:217], v[40:43]
	v_mfma_f32_16x16x32_bf16 v[28:31], v[144:147], v[222:225], v[28:31]
	v_mfma_f32_16x16x32_bf16 v[24:27], v[168:171], v[222:225], v[24:27]
	v_mfma_f32_16x16x32_bf16 v[12:15], v[144:147], v[230:233], v[12:15]
	v_mfma_f32_16x16x32_bf16 v[8:11], v[168:171], v[230:233], v[8:11]
	v_mfma_f32_16x16x32_bf16 v[60:63], v[164:167], v[210:213], v[60:63]
	v_mfma_f32_16x16x32_bf16 v[56:59], v[186:189], v[210:213], v[56:59]
	v_mfma_f32_16x16x32_bf16 v[44:47], v[164:167], v[218:221], v[44:47]
	v_mfma_f32_16x16x32_bf16 v[40:43], v[186:189], v[218:221], v[40:43]
	v_mfma_f32_16x16x32_bf16 v[28:31], v[164:167], v[226:229], v[28:31]
	v_mfma_f32_16x16x32_bf16 v[24:27], v[186:189], v[226:229], v[24:27]
	v_mfma_f32_16x16x32_bf16 v[12:15], v[164:167], v[242:245], v[12:15]
	v_mfma_f32_16x16x32_bf16 v[8:11], v[186:189], v[242:245], v[8:11]
	s_setprio 0
	s_setprio 1
	v_mfma_f32_16x16x32_bf16 v[52:55], v[190:193], v[206:209], v[52:55]
	v_mfma_f32_16x16x32_bf16 v[48:51], v[198:201], v[206:209], v[48:51]
	v_mfma_f32_16x16x32_bf16 v[36:39], v[190:193], v[214:217], v[36:39]
	v_mfma_f32_16x16x32_bf16 v[32:35], v[198:201], v[214:217], v[32:35]
	v_mfma_f32_16x16x32_bf16 v[20:23], v[190:193], v[222:225], v[20:23]
	v_mfma_f32_16x16x32_bf16 v[16:19], v[198:201], v[222:225], v[16:19]
	v_mfma_f32_16x16x32_bf16 v[4:7], v[190:193], v[230:233], v[4:7]
	v_mfma_f32_16x16x32_bf16 v[0:3], v[198:201], v[230:233], v[0:3]
	v_mfma_f32_16x16x32_bf16 v[52:55], v[194:197], v[210:213], v[52:55]
	v_mfma_f32_16x16x32_bf16 v[48:51], v[202:205], v[210:213], v[48:51]
	v_mfma_f32_16x16x32_bf16 v[36:39], v[194:197], v[218:221], v[36:39]
	v_mfma_f32_16x16x32_bf16 v[32:35], v[202:205], v[218:221], v[32:35]
	v_mfma_f32_16x16x32_bf16 v[20:23], v[194:197], v[226:229], v[20:23]
	v_mfma_f32_16x16x32_bf16 v[16:19], v[202:205], v[226:229], v[16:19]
	v_mfma_f32_16x16x32_bf16 v[4:7], v[194:197], v[242:245], v[4:7]
	v_mfma_f32_16x16x32_bf16 v[0:3], v[202:205], v[242:245], v[0:3]
	s_setprio 2
	s_barrier
	s_add_i32 s60, 0, 0x18000
	v_add_u32_e32 v96, s60, v151
	s_add_i32 s61, 0, 0x1c000
	ds_read_b128 v[144:147], v96
	ds_read_b128 v[164:167], v96 offset:1024
	ds_read_b128 v[168:171], v96 offset:2048
	ds_read_b128 v[186:189], v96 offset:3072
	v_add_u32_e32 v96, s61, v151
	ds_read_b128 v[190:193], v96
	ds_read_b128 v[194:197], v96 offset:1024
	ds_read_b128 v[198:201], v96 offset:2048
	ds_read_b128 v[202:205], v96 offset:3072
	s_add_u32 s34, s34, 0x40000
	s_addc_u32 s35, s35, 0
	s_mov_b32 m0, s43
	v_lshl_add_u64 v[172:173], s[34:35], 0, v[136:137]
	ds_read_b128 v[206:209], v163 offset:32768
	ds_read_b128 v[210:213], v163 offset:33792
	ds_read_b128 v[214:217], v163 offset:34816
	ds_read_b128 v[218:221], v163 offset:35840
	ds_read_b128 v[222:225], v163 offset:36864
	ds_read_b128 v[226:229], v163 offset:37888
	ds_read_b128 v[230:233], v163 offset:38912
	ds_read_b128 v[242:245], v163 offset:39936
	global_load_lds_dwordx4 v[172:173], off
	v_lshl_add_u64 v[172:173], s[34:35], 0, v[132:133]
	s_mov_b32 m0, s44
	s_nop 0
	global_load_lds_dwordx4 v[172:173], off
	s_setprio 1
	s_waitcnt vmcnt(8) lgkmcnt(0)
	s_barrier
	v_mfma_f32_16x16x32_bf16 v[126:129], v[144:147], v[206:209], v[126:129]
	v_mfma_f32_16x16x32_bf16 v[122:125], v[168:171], v[206:209], v[122:125]
	v_mfma_f32_16x16x32_bf16 v[110:113], v[144:147], v[214:217], v[110:113]
	v_mfma_f32_16x16x32_bf16 v[106:109], v[168:171], v[214:217], v[106:109]
	v_mfma_f32_16x16x32_bf16 v[92:95], v[144:147], v[222:225], v[92:95]
	v_mfma_f32_16x16x32_bf16 v[88:91], v[168:171], v[222:225], v[88:91]
	v_mfma_f32_16x16x32_bf16 v[76:79], v[144:147], v[230:233], v[76:79]
	v_mfma_f32_16x16x32_bf16 v[72:75], v[168:171], v[230:233], v[72:75]
	v_mfma_f32_16x16x32_bf16 v[126:129], v[164:167], v[210:213], v[126:129]
	v_mfma_f32_16x16x32_bf16 v[122:125], v[186:189], v[210:213], v[122:125]
	v_mfma_f32_16x16x32_bf16 v[110:113], v[164:167], v[218:221], v[110:113]
	v_mfma_f32_16x16x32_bf16 v[106:109], v[186:189], v[218:221], v[106:109]
	v_mfma_f32_16x16x32_bf16 v[92:95], v[164:167], v[226:229], v[92:95]
	v_mfma_f32_16x16x32_bf16 v[88:91], v[186:189], v[226:229], v[88:91]
	v_mfma_f32_16x16x32_bf16 v[76:79], v[164:167], v[242:245], v[76:79]
	v_mfma_f32_16x16x32_bf16 v[72:75], v[186:189], v[242:245], v[72:75]
	s_setprio 0
	s_setprio 1
	v_mfma_f32_16x16x32_bf16 v[118:121], v[190:193], v[206:209], v[118:121]
	v_mfma_f32_16x16x32_bf16 v[114:117], v[198:201], v[206:209], v[114:117]
	v_mfma_f32_16x16x32_bf16 v[102:105], v[190:193], v[214:217], v[102:105]
	v_mfma_f32_16x16x32_bf16 v[98:101], v[198:201], v[214:217], v[98:101]
	v_mfma_f32_16x16x32_bf16 v[84:87], v[190:193], v[222:225], v[84:87]
	v_mfma_f32_16x16x32_bf16 v[80:83], v[198:201], v[222:225], v[80:83]
	v_mfma_f32_16x16x32_bf16 v[68:71], v[190:193], v[230:233], v[68:71]
	v_mfma_f32_16x16x32_bf16 v[64:67], v[198:201], v[230:233], v[64:67]
	v_mfma_f32_16x16x32_bf16 v[118:121], v[194:197], v[210:213], v[118:121]
	v_mfma_f32_16x16x32_bf16 v[114:117], v[202:205], v[210:213], v[114:117]
	v_mfma_f32_16x16x32_bf16 v[102:105], v[194:197], v[218:221], v[102:105]
	v_mfma_f32_16x16x32_bf16 v[98:101], v[202:205], v[218:221], v[98:101]
	v_mfma_f32_16x16x32_bf16 v[84:87], v[194:197], v[226:229], v[84:87]
	v_mfma_f32_16x16x32_bf16 v[80:83], v[202:205], v[226:229], v[80:83]
	v_mfma_f32_16x16x32_bf16 v[68:71], v[194:197], v[242:245], v[68:71]
	v_mfma_f32_16x16x32_bf16 v[64:67], v[202:205], v[242:245], v[64:67]
	s_setprio 2
	s_barrier
	s_add_i32 s34, s60, s40
	v_lshl_add_u64 v[148:149], v[148:149], 0, s[16:17]
	s_mov_b32 m0, s34
	ds_read_b128 v[206:209], v163 offset:49152
	ds_read_b128 v[210:213], v163 offset:50176
	ds_read_b128 v[214:217], v163 offset:51200
	ds_read_b128 v[218:221], v163 offset:52224
	ds_read_b128 v[222:225], v163 offset:53248
	ds_read_b128 v[226:229], v163 offset:54272
	ds_read_b128 v[230:233], v163 offset:55296
	ds_read_b128 v[242:245], v163 offset:56320
	global_load_lds_dwordx4 v[148:149], off
	s_add_i32 m0, s34, 0x2000
	s_add_u32 s30, s30, 0x40080
	v_lshl_add_u64 v[148:149], v[154:155], 0, s[16:17]
	s_addc_u32 s31, s31, 0
	s_add_i32 s34, s61, s40
	global_load_lds_dwordx4 v[148:149], off
	v_lshl_add_u64 v[148:149], s[30:31], 0, v[134:135]
	s_mov_b32 m0, s34
	s_nop 0
	global_load_lds_dwordx4 v[148:149], off
	v_lshl_add_u64 v[148:149], s[30:31], 0, v[130:131]
	s_add_i32 m0, s34, 0x2000
	s_nop 0
	global_load_lds_dwordx4 v[148:149], off
	v_lshl_add_u64 v[148:149], v[156:157], 0, s[16:17]
	s_mov_b32 m0, s49
	s_nop 0
	global_load_lds_dwordx4 v[148:149], off
	v_lshl_add_u64 v[148:149], v[158:159], 0, s[16:17]
	s_mov_b32 m0, s50
	s_nop 0
	global_load_lds_dwordx4 v[148:149], off
	s_setprio 1
	s_waitcnt vmcnt(8) lgkmcnt(0)
	s_barrier
	v_mfma_f32_16x16x32_bf16 v[60:63], v[144:147], v[206:209], v[60:63]
	v_mfma_f32_16x16x32_bf16 v[56:59], v[168:171], v[206:209], v[56:59]
	v_mfma_f32_16x16x32_bf16 v[44:47], v[144:147], v[214:217], v[44:47]
	v_mfma_f32_16x16x32_bf16 v[40:43], v[168:171], v[214:217], v[40:43]
	v_mfma_f32_16x16x32_bf16 v[28:31], v[144:147], v[222:225], v[28:31]
	v_mfma_f32_16x16x32_bf16 v[24:27], v[168:171], v[222:225], v[24:27]
	v_mfma_f32_16x16x32_bf16 v[12:15], v[144:147], v[230:233], v[12:15]
	v_mfma_f32_16x16x32_bf16 v[8:11], v[168:171], v[230:233], v[8:11]
	v_mfma_f32_16x16x32_bf16 v[60:63], v[164:167], v[210:213], v[60:63]
	v_mfma_f32_16x16x32_bf16 v[56:59], v[186:189], v[210:213], v[56:59]
	v_mfma_f32_16x16x32_bf16 v[44:47], v[164:167], v[218:221], v[44:47]
	v_mfma_f32_16x16x32_bf16 v[40:43], v[186:189], v[218:221], v[40:43]
	v_mfma_f32_16x16x32_bf16 v[28:31], v[164:167], v[226:229], v[28:31]
	v_mfma_f32_16x16x32_bf16 v[24:27], v[186:189], v[226:229], v[24:27]
	v_mfma_f32_16x16x32_bf16 v[12:15], v[164:167], v[242:245], v[12:15]
	v_mfma_f32_16x16x32_bf16 v[8:11], v[186:189], v[242:245], v[8:11]
	s_setprio 0
	s_setprio 1
	v_mfma_f32_16x16x32_bf16 v[52:55], v[190:193], v[206:209], v[52:55]
	v_mfma_f32_16x16x32_bf16 v[48:51], v[198:201], v[206:209], v[48:51]
	v_mfma_f32_16x16x32_bf16 v[36:39], v[190:193], v[214:217], v[36:39]
	v_mfma_f32_16x16x32_bf16 v[32:35], v[198:201], v[214:217], v[32:35]
	v_mfma_f32_16x16x32_bf16 v[20:23], v[190:193], v[222:225], v[20:23]
	v_mfma_f32_16x16x32_bf16 v[16:19], v[198:201], v[222:225], v[16:19]
	v_mfma_f32_16x16x32_bf16 v[4:7], v[190:193], v[230:233], v[4:7]
	v_mfma_f32_16x16x32_bf16 v[0:3], v[198:201], v[230:233], v[0:3]
	v_mfma_f32_16x16x32_bf16 v[52:55], v[194:197], v[210:213], v[52:55]
	v_mfma_f32_16x16x32_bf16 v[48:51], v[202:205], v[210:213], v[48:51]
	v_mfma_f32_16x16x32_bf16 v[36:39], v[194:197], v[218:221], v[36:39]
	v_mfma_f32_16x16x32_bf16 v[32:35], v[202:205], v[218:221], v[32:35]
	v_mfma_f32_16x16x32_bf16 v[20:23], v[194:197], v[226:229], v[20:23]
	v_mfma_f32_16x16x32_bf16 v[16:19], v[202:205], v[226:229], v[16:19]
	v_mfma_f32_16x16x32_bf16 v[4:7], v[194:197], v[242:245], v[4:7]
	v_mfma_f32_16x16x32_bf16 v[0:3], v[202:205], v[242:245], v[0:3]
	s_setprio 2
	s_barrier
	s_add_i32 s59, s59, 2
	s_add_u32 s14, s14, 0x100
	s_addc_u32 s15, s15, 0
	s_add_u32 s57, s57, 0x100
	s_addc_u32 s58, s58, 0
	s_cmp_gt_u32 s59, 13
	s_cbranch_scc0 .LBB0_449
	s_and_b64 vcc, exec, s[18:19]
	s_cbranch_vccz .LBB0_454
	s_barrier
	v_lshl_add_u32 v146, s54, 8, v150
	s_cmp_gt_i32 s53, 7
	s_mov_b64 s[14:15], -1
	s_cbranch_scc1 .LBB0_455

.LBB0_490:
	s_add_i32 s66, s6, 2
	s_add_u32 s67, s4, 0x80
	s_addc_u32 s7, s5, 0
	s_add_i32 s70, 0, 0x10000
	s_cmp_eq_u32 s60, s6
	s_cselect_b32 s7, s43, s7
	s_cselect_b32 s6, s42, s67
	v_add_u32_e32 v148, s70, v151
	s_cselect_b32 s69, s45, s15
	s_cselect_b32 s68, s44, s14
	s_add_i32 s67, 0, 0x14000
	ds_read_b128 v[140:143], v148
	ds_read_b128 v[144:147], v148 offset:1024
	ds_read_b128 v[162:165], v148 offset:2048
	ds_read_b128 v[166:169], v148 offset:3072
	v_add_u32_e32 v148, s67, v151
	ds_read_b128 v[170:173], v148
	ds_read_b128 v[186:189], v148 offset:1024
	ds_read_b128 v[190:193], v148 offset:2048
	ds_read_b128 v[194:197], v148 offset:3072
	v_lshl_add_u64 v[148:149], s[4:5], 0, v[136:137]
	s_add_i32 m0, s52, 0xc000
	ds_read_b128 v[198:201], v153
	ds_read_b128 v[202:205], v153 offset:1024
	ds_read_b128 v[206:209], v153 offset:2048
	ds_read_b128 v[210:213], v153 offset:3072
	ds_read_b128 v[214:217], v153 offset:4096
	ds_read_b128 v[218:221], v153 offset:5120
	ds_read_b128 v[222:225], v153 offset:6144
	ds_read_b128 v[226:229], v153 offset:7168
	global_load_lds_dwordx4 v[148:149], off
	v_lshl_add_u64 v[148:149], s[4:5], 0, v[138:139]
	s_add_i32 m0, s52, 0xe000
	s_nop 0
	global_load_lds_dwordx4 v[148:149], off
	s_setprio 1
	s_waitcnt vmcnt(8) lgkmcnt(0)
	s_barrier
	v_mfma_f32_16x16x32_bf16 v[126:129], v[140:143], v[198:201], v[126:129]
	v_mfma_f32_16x16x32_bf16 v[122:125], v[162:165], v[198:201], v[122:125]
	v_mfma_f32_16x16x32_bf16 v[110:113], v[140:143], v[206:209], v[110:113]
	v_mfma_f32_16x16x32_bf16 v[106:109], v[162:165], v[206:209], v[106:109]
	v_mfma_f32_16x16x32_bf16 v[92:95], v[140:143], v[214:217], v[92:95]
	v_mfma_f32_16x16x32_bf16 v[88:91], v[162:165], v[214:217], v[88:91]
	v_mfma_f32_16x16x32_bf16 v[76:79], v[140:143], v[222:225], v[76:79]
	v_mfma_f32_16x16x32_bf16 v[72:75], v[162:165], v[222:225], v[72:75]
	v_mfma_f32_16x16x32_bf16 v[126:129], v[144:147], v[202:205], v[126:129]
	v_mfma_f32_16x16x32_bf16 v[122:125], v[166:169], v[202:205], v[122:125]
	v_mfma_f32_16x16x32_bf16 v[110:113], v[144:147], v[210:213], v[110:113]
	v_mfma_f32_16x16x32_bf16 v[106:109], v[166:169], v[210:213], v[106:109]
	v_mfma_f32_16x16x32_bf16 v[92:95], v[144:147], v[218:221], v[92:95]
	v_mfma_f32_16x16x32_bf16 v[88:91], v[166:169], v[218:221], v[88:91]
	v_mfma_f32_16x16x32_bf16 v[76:79], v[144:147], v[226:229], v[76:79]
	v_mfma_f32_16x16x32_bf16 v[72:75], v[166:169], v[226:229], v[72:75]
	s_setprio 0
	s_setprio 1
	v_mfma_f32_16x16x32_bf16 v[118:121], v[170:173], v[198:201], v[118:121]
	v_mfma_f32_16x16x32_bf16 v[114:117], v[190:193], v[198:201], v[114:117]
	v_mfma_f32_16x16x32_bf16 v[102:105], v[170:173], v[206:209], v[102:105]
	v_mfma_f32_16x16x32_bf16 v[98:101], v[190:193], v[206:209], v[98:101]
	v_mfma_f32_16x16x32_bf16 v[84:87], v[170:173], v[214:217], v[84:87]
	v_mfma_f32_16x16x32_bf16 v[80:83], v[190:193], v[214:217], v[80:83]
	v_mfma_f32_16x16x32_bf16 v[68:71], v[170:173], v[222:225], v[68:71]
	v_mfma_f32_16x16x32_bf16 v[64:67], v[190:193], v[222:225], v[64:67]
	v_mfma_f32_16x16x32_bf16 v[118:121], v[186:189], v[202:205], v[118:121]
	v_mfma_f32_16x16x32_bf16 v[114:117], v[194:197], v[202:205], v[114:117]
	v_mfma_f32_16x16x32_bf16 v[102:105], v[186:189], v[210:213], v[102:105]
	v_mfma_f32_16x16x32_bf16 v[98:101], v[194:197], v[210:213], v[98:101]
	v_mfma_f32_16x16x32_bf16 v[84:87], v[186:189], v[218:221], v[84:87]
	v_mfma_f32_16x16x32_bf16 v[80:83], v[194:197], v[218:221], v[80:83]
	v_mfma_f32_16x16x32_bf16 v[68:71], v[186:189], v[226:229], v[68:71]
	v_mfma_f32_16x16x32_bf16 v[64:67], v[194:197], v[226:229], v[64:67]
	s_setprio 2
	s_barrier
	s_add_i32 s70, s70, s51
	v_lshl_add_u64 v[148:149], s[68:69], 0, v[96:97]
	s_mov_b32 m0, s70
	ds_read_b128 v[198:201], v153 offset:16384
	ds_read_b128 v[202:205], v153 offset:17408
	ds_read_b128 v[206:209], v153 offset:18432
	ds_read_b128 v[210:213], v153 offset:19456
	ds_read_b128 v[214:217], v153 offset:20480
	ds_read_b128 v[218:221], v153 offset:21504
	ds_read_b128 v[222:225], v153 offset:22528
	ds_read_b128 v[226:229], v153 offset:23552
	global_load_lds_dwordx4 v[148:149], off
	s_add_i32 m0, s70, 0x2000
	v_lshl_add_u64 v[154:155], s[68:69], 0, v[130:131]
	s_add_u32 s68, s68, s46
	s_addc_u32 s69, s69, 0
	s_add_i32 s67, s67, s51
	global_load_lds_dwordx4 v[154:155], off
	v_lshl_add_u64 v[156:157], s[68:69], 0, v[96:97]
	s_mov_b32 m0, s67
	v_lshl_add_u64 v[158:159], s[68:69], 0, v[130:131]
	global_load_lds_dwordx4 v[156:157], off
	s_add_i32 m0, s67, 0x2000
	v_lshl_add_u64 v[182:183], s[6:7], 0, v[134:135]
	global_load_lds_dwordx4 v[158:159], off
	s_mov_b32 m0, s52
	v_lshl_add_u64 v[184:185], s[6:7], 0, v[132:133]
	global_load_lds_dwordx4 v[182:183], off
	s_mov_b32 m0, s53
	s_nop 0
	global_load_lds_dwordx4 v[184:185], off
	s_setprio 1
	s_waitcnt vmcnt(8) lgkmcnt(0)
	s_barrier
	v_mfma_f32_16x16x32_bf16 v[60:63], v[140:143], v[198:201], v[60:63]
	v_mfma_f32_16x16x32_bf16 v[56:59], v[162:165], v[198:201], v[56:59]
	v_mfma_f32_16x16x32_bf16 v[44:47], v[140:143], v[206:209], v[44:47]
	v_mfma_f32_16x16x32_bf16 v[40:43], v[162:165], v[206:209], v[40:43]
	v_mfma_f32_16x16x32_bf16 v[28:31], v[140:143], v[214:217], v[28:31]
	v_mfma_f32_16x16x32_bf16 v[24:27], v[162:165], v[214:217], v[24:27]
	v_mfma_f32_16x16x32_bf16 v[12:15], v[140:143], v[222:225], v[12:15]
	v_mfma_f32_16x16x32_bf16 v[8:11], v[162:165], v[222:225], v[8:11]
	v_mfma_f32_16x16x32_bf16 v[60:63], v[144:147], v[202:205], v[60:63]
	v_mfma_f32_16x16x32_bf16 v[56:59], v[166:169], v[202:205], v[56:59]
	v_mfma_f32_16x16x32_bf16 v[44:47], v[144:147], v[210:213], v[44:47]
	v_mfma_f32_16x16x32_bf16 v[40:43], v[166:169], v[210:213], v[40:43]
	v_mfma_f32_16x16x32_bf16 v[28:31], v[144:147], v[218:221], v[28:31]
	v_mfma_f32_16x16x32_bf16 v[24:27], v[166:169], v[218:221], v[24:27]
	v_mfma_f32_16x16x32_bf16 v[12:15], v[144:147], v[226:229], v[12:15]
	v_mfma_f32_16x16x32_bf16 v[8:11], v[166:169], v[226:229], v[8:11]
	s_setprio 0
	s_setprio 1
	v_mfma_f32_16x16x32_bf16 v[52:55], v[170:173], v[198:201], v[52:55]
	v_mfma_f32_16x16x32_bf16 v[48:51], v[190:193], v[198:201], v[48:51]
	v_mfma_f32_16x16x32_bf16 v[36:39], v[170:173], v[206:209], v[36:39]
	v_mfma_f32_16x16x32_bf16 v[32:35], v[190:193], v[206:209], v[32:35]
	v_mfma_f32_16x16x32_bf16 v[20:23], v[170:173], v[214:217], v[20:23]
	v_mfma_f32_16x16x32_bf16 v[16:19], v[190:193], v[214:217], v[16:19]
	v_mfma_f32_16x16x32_bf16 v[4:7], v[170:173], v[222:225], v[4:7]
	v_mfma_f32_16x16x32_bf16 v[0:3], v[190:193], v[222:225], v[0:3]
	v_mfma_f32_16x16x32_bf16 v[52:55], v[186:189], v[202:205], v[52:55]
	v_mfma_f32_16x16x32_bf16 v[48:51], v[194:197], v[202:205], v[48:51]
	v_mfma_f32_16x16x32_bf16 v[36:39], v[186:189], v[210:213], v[36:39]
	v_mfma_f32_16x16x32_bf16 v[32:35], v[194:197], v[210:213], v[32:35]
	v_mfma_f32_16x16x32_bf16 v[20:23], v[186:189], v[218:221], v[20:23]
	v_mfma_f32_16x16x32_bf16 v[16:19], v[194:197], v[218:221], v[16:19]
	v_mfma_f32_16x16x32_bf16 v[4:7], v[186:189], v[226:229], v[4:7]
	v_mfma_f32_16x16x32_bf16 v[0:3], v[194:197], v[226:229], v[0:3]
	s_setprio 2
	s_barrier
	s_add_i32 s67, 0, 0x18000
	s_add_i32 s68, 0, 0x1c000
	v_add_u32_e32 v166, s67, v151
	v_add_u32_e32 v194, s68, v151
	ds_read_b128 v[140:143], v166
	ds_read_b128 v[144:147], v166 offset:1024
	ds_read_b128 v[162:165], v166 offset:2048
	ds_read_b128 v[166:169], v166 offset:3072
	ds_read_b128 v[170:173], v194
	ds_read_b128 v[186:189], v194 offset:1024
	ds_read_b128 v[190:193], v194 offset:2048
	ds_read_b128 v[194:197], v194 offset:3072
	s_add_u32 s6, s6, s46
	s_addc_u32 s7, s7, 0
	s_mov_b32 m0, s54
	v_lshl_add_u64 v[230:231], s[6:7], 0, v[134:135]
	ds_read_b128 v[198:201], v153 offset:32768
	ds_read_b128 v[202:205], v153 offset:33792
	ds_read_b128 v[206:209], v153 offset:34816
	ds_read_b128 v[210:213], v153 offset:35840
	ds_read_b128 v[214:217], v153 offset:36864
	ds_read_b128 v[218:221], v153 offset:37888
	ds_read_b128 v[222:225], v153 offset:38912
	ds_read_b128 v[226:229], v153 offset:39936
	global_load_lds_dwordx4 v[230:231], off
	v_lshl_add_u64 v[230:231], s[6:7], 0, v[132:133]
	s_mov_b32 m0, s55
	s_nop 0
	global_load_lds_dwordx4 v[230:231], off
	s_setprio 1
	s_waitcnt vmcnt(8) lgkmcnt(0)
	s_barrier
	v_mfma_f32_16x16x32_bf16 v[126:129], v[140:143], v[198:201], v[126:129]
	v_mfma_f32_16x16x32_bf16 v[122:125], v[162:165], v[198:201], v[122:125]
	v_mfma_f32_16x16x32_bf16 v[110:113], v[140:143], v[206:209], v[110:113]
	v_mfma_f32_16x16x32_bf16 v[106:109], v[162:165], v[206:209], v[106:109]
	v_mfma_f32_16x16x32_bf16 v[92:95], v[140:143], v[214:217], v[92:95]
	v_mfma_f32_16x16x32_bf16 v[88:91], v[162:165], v[214:217], v[88:91]
	v_mfma_f32_16x16x32_bf16 v[76:79], v[140:143], v[222:225], v[76:79]
	v_mfma_f32_16x16x32_bf16 v[72:75], v[162:165], v[222:225], v[72:75]
	v_mfma_f32_16x16x32_bf16 v[126:129], v[144:147], v[202:205], v[126:129]
	v_mfma_f32_16x16x32_bf16 v[122:125], v[166:169], v[202:205], v[122:125]
	v_mfma_f32_16x16x32_bf16 v[110:113], v[144:147], v[210:213], v[110:113]
	v_mfma_f32_16x16x32_bf16 v[106:109], v[166:169], v[210:213], v[106:109]
	v_mfma_f32_16x16x32_bf16 v[92:95], v[144:147], v[218:221], v[92:95]
	v_mfma_f32_16x16x32_bf16 v[88:91], v[166:169], v[218:221], v[88:91]
	v_mfma_f32_16x16x32_bf16 v[76:79], v[144:147], v[226:229], v[76:79]
	v_mfma_f32_16x16x32_bf16 v[72:75], v[166:169], v[226:229], v[72:75]
	s_setprio 0
	s_setprio 1
	v_mfma_f32_16x16x32_bf16 v[118:121], v[170:173], v[198:201], v[118:121]
	v_mfma_f32_16x16x32_bf16 v[114:117], v[190:193], v[198:201], v[114:117]
	v_mfma_f32_16x16x32_bf16 v[102:105], v[170:173], v[206:209], v[102:105]
	v_mfma_f32_16x16x32_bf16 v[98:101], v[190:193], v[206:209], v[98:101]
	v_mfma_f32_16x16x32_bf16 v[84:87], v[170:173], v[214:217], v[84:87]
	v_mfma_f32_16x16x32_bf16 v[80:83], v[190:193], v[214:217], v[80:83]
	v_mfma_f32_16x16x32_bf16 v[68:71], v[170:173], v[222:225], v[68:71]
	v_mfma_f32_16x16x32_bf16 v[64:67], v[190:193], v[222:225], v[64:67]
	v_mfma_f32_16x16x32_bf16 v[118:121], v[186:189], v[202:205], v[118:121]
	v_mfma_f32_16x16x32_bf16 v[114:117], v[194:197], v[202:205], v[114:117]
	v_mfma_f32_16x16x32_bf16 v[102:105], v[186:189], v[210:213], v[102:105]
	v_mfma_f32_16x16x32_bf16 v[98:101], v[194:197], v[210:213], v[98:101]
	v_mfma_f32_16x16x32_bf16 v[84:87], v[186:189], v[218:221], v[84:87]
	v_mfma_f32_16x16x32_bf16 v[80:83], v[194:197], v[218:221], v[80:83]
	v_mfma_f32_16x16x32_bf16 v[68:71], v[186:189], v[226:229], v[68:71]
	v_mfma_f32_16x16x32_bf16 v[64:67], v[194:197], v[226:229], v[64:67]
	s_setprio 2
	s_barrier
	s_add_i32 s6, s67, s51
	v_lshl_add_u64 v[148:149], v[148:149], 0, s[16:17]
	s_mov_b32 m0, s6
	ds_read_b128 v[198:201], v153 offset:49152
	ds_read_b128 v[202:205], v153 offset:50176
	ds_read_b128 v[206:209], v153 offset:51200
	ds_read_b128 v[210:213], v153 offset:52224
	ds_read_b128 v[214:217], v153 offset:53248
	ds_read_b128 v[218:221], v153 offset:54272
	ds_read_b128 v[222:225], v153 offset:55296
	ds_read_b128 v[226:229], v153 offset:56320
	global_load_lds_dwordx4 v[148:149], off
	v_lshl_add_u64 v[148:149], v[154:155], 0, s[16:17]
	s_add_i32 m0, s6, 0x2000
	s_add_i32 s6, s68, s51
	global_load_lds_dwordx4 v[148:149], off
	v_lshl_add_u64 v[148:149], v[156:157], 0, s[16:17]
	s_mov_b32 m0, s6
	s_nop 0
	global_load_lds_dwordx4 v[148:149], off
	v_lshl_add_u64 v[148:149], v[158:159], 0, s[16:17]
	s_add_i32 m0, s6, 0x2000
	s_nop 0
	global_load_lds_dwordx4 v[148:149], off
	v_lshl_add_u64 v[148:149], v[182:183], 0, s[16:17]
	s_mov_b32 m0, s56
	s_nop 0
	global_load_lds_dwordx4 v[148:149], off
	v_lshl_add_u64 v[148:149], v[184:185], 0, s[16:17]
	s_mov_b32 m0, s57
	s_nop 0
	global_load_lds_dwordx4 v[148:149], off
	s_setprio 1
	s_waitcnt vmcnt(8) lgkmcnt(0)
	s_barrier
	v_mfma_f32_16x16x32_bf16 v[60:63], v[140:143], v[198:201], v[60:63]
	v_mfma_f32_16x16x32_bf16 v[56:59], v[162:165], v[198:201], v[56:59]
	v_mfma_f32_16x16x32_bf16 v[44:47], v[140:143], v[206:209], v[44:47]
	v_mfma_f32_16x16x32_bf16 v[40:43], v[162:165], v[206:209], v[40:43]
	v_mfma_f32_16x16x32_bf16 v[28:31], v[140:143], v[214:217], v[28:31]
	v_mfma_f32_16x16x32_bf16 v[24:27], v[162:165], v[214:217], v[24:27]
	v_mfma_f32_16x16x32_bf16 v[12:15], v[140:143], v[222:225], v[12:15]
	v_mfma_f32_16x16x32_bf16 v[8:11], v[162:165], v[222:225], v[8:11]
	v_mfma_f32_16x16x32_bf16 v[60:63], v[144:147], v[202:205], v[60:63]
	v_mfma_f32_16x16x32_bf16 v[56:59], v[166:169], v[202:205], v[56:59]
	v_mfma_f32_16x16x32_bf16 v[44:47], v[144:147], v[210:213], v[44:47]
	v_mfma_f32_16x16x32_bf16 v[40:43], v[166:169], v[210:213], v[40:43]
	v_mfma_f32_16x16x32_bf16 v[28:31], v[144:147], v[218:221], v[28:31]
	v_mfma_f32_16x16x32_bf16 v[24:27], v[166:169], v[218:221], v[24:27]
	v_mfma_f32_16x16x32_bf16 v[12:15], v[144:147], v[226:229], v[12:15]
	v_mfma_f32_16x16x32_bf16 v[8:11], v[166:169], v[226:229], v[8:11]
	s_setprio 0
	s_setprio 1
	v_mfma_f32_16x16x32_bf16 v[52:55], v[170:173], v[198:201], v[52:55]
	v_mfma_f32_16x16x32_bf16 v[48:51], v[190:193], v[198:201], v[48:51]
	v_mfma_f32_16x16x32_bf16 v[36:39], v[170:173], v[206:209], v[36:39]
	v_mfma_f32_16x16x32_bf16 v[32:35], v[190:193], v[206:209], v[32:35]
	v_mfma_f32_16x16x32_bf16 v[20:23], v[170:173], v[214:217], v[20:23]
	v_mfma_f32_16x16x32_bf16 v[16:19], v[190:193], v[214:217], v[16:19]
	v_mfma_f32_16x16x32_bf16 v[4:7], v[170:173], v[222:225], v[4:7]
	v_mfma_f32_16x16x32_bf16 v[0:3], v[190:193], v[222:225], v[0:3]
	v_mfma_f32_16x16x32_bf16 v[52:55], v[186:189], v[202:205], v[52:55]
	v_mfma_f32_16x16x32_bf16 v[48:51], v[194:197], v[202:205], v[48:51]
	v_mfma_f32_16x16x32_bf16 v[36:39], v[186:189], v[210:213], v[36:39]
	v_mfma_f32_16x16x32_bf16 v[32:35], v[194:197], v[210:213], v[32:35]
	v_mfma_f32_16x16x32_bf16 v[20:23], v[186:189], v[218:221], v[20:23]
	v_mfma_f32_16x16x32_bf16 v[16:19], v[194:197], v[218:221], v[16:19]
	v_mfma_f32_16x16x32_bf16 v[4:7], v[186:189], v[226:229], v[4:7]
	v_mfma_f32_16x16x32_bf16 v[0:3], v[194:197], v[226:229], v[0:3]
	s_setprio 2
	s_barrier
	s_add_u32 s4, s4, 0x100
	s_addc_u32 s5, s5, 0
	s_add_u32 s14, s14, 0x100
	s_addc_u32 s15, s15, 0
	s_cmp_ge_u32 s66, s59
	s_mov_b32 s6, s66
	s_cbranch_scc0 .LBB0_490
	s_and_b64 vcc, exec, s[36:37]
	s_cbranch_vccz .LBB0_493
	s_barrier
